# RWKV scan step: the 4-op dependent y chain interleaved with the state updates that feed it (same instructions, bit-identical)
# speedup vs baseline: 1.0027x; 1.0027x over previous
.Lrc_chunk:
	s_cmp_gt_u32 s34, 3
	s_cbranch_scc1 .Lrc_stage
	ds_read_b128 v[134:137], v42 offset:768
	ds_read_b128 v[130:133], v42 offset:512
	ds_read_b64 v[142:143], v43 offset:0
	ds_read_b128 v[122:125], v42 offset:0
	ds_read_b128 v[126:129], v42 offset:256
	ds_read_b128 v[138:141], v42 offset:1024
	s_waitcnt lgkmcnt(0)
	ds_read_b128 v[166:169], v42 offset:2304
	ds_read_b128 v[162:165], v42 offset:2048
	ds_read_b64 v[174:175], v43 offset:1536
	ds_read_b128 v[154:157], v42 offset:1536
	ds_read_b128 v[158:161], v42 offset:1792
	ds_read_b128 v[170:173], v42 offset:2560
	v_pk_mul_f32 v[198:199], v[2:3], v[134:135] op_sel:[0,0] op_sel_hi:[1,0]
	v_pk_mul_f32 v[176:177], v[142:143], v[130:131] op_sel:[0,0] op_sel_hi:[1,0]
	v_pk_fma_f32 v[198:199], v[4:5], v[134:135], v[198:199] op_sel:[0,1,0] op_sel_hi:[1,1,1]
	v_pk_mul_f32 v[178:179], v[142:143], v[130:131] op_sel:[0,1] op_sel_hi:[1,1]
	v_pk_fma_f32 v[198:199], v[6:7], v[136:137], v[198:199] op_sel:[0,0,0] op_sel_hi:[1,0,1]
	v_pk_mul_f32 v[180:181], v[142:143], v[132:133] op_sel:[0,0] op_sel_hi:[1,0]
	v_pk_fma_f32 v[198:199], v[8:9], v[136:137], v[198:199] op_sel:[0,1,0] op_sel_hi:[1,1,1]
	v_pk_mul_f32 v[188:189], v[142:143], v[132:133] op_sel:[0,1] op_sel_hi:[1,1]
	v_pk_fma_f32 v[2:3], v[2:3], v[122:123], v[176:177] op_sel:[0,0,0] op_sel_hi:[1,0,1]
	v_add_f32_dpp v198, v198, v198 quad_perm:[1,0,3,2] row_mask:0xf bank_mask:0xf bound_ctrl:1
	v_add_f32_dpp v199, v199, v199 quad_perm:[1,0,3,2] row_mask:0xf bank_mask:0xf bound_ctrl:1
	v_pk_fma_f32 v[4:5], v[4:5], v[122:123], v[178:179] op_sel:[0,1,0] op_sel_hi:[1,1,1]
	v_add_f32_dpp v198, v198, v198 quad_perm:[2,3,0,1] row_mask:0xf bank_mask:0xf bound_ctrl:1
	v_add_f32_dpp v199, v199, v199 quad_perm:[2,3,0,1] row_mask:0xf bank_mask:0xf bound_ctrl:1
	v_pk_fma_f32 v[6:7], v[6:7], v[124:125], v[180:181] op_sel:[0,0,0] op_sel_hi:[1,0,1]
	v_add_f32_dpp v198, v198, v198 row_half_mirror row_mask:0xf bank_mask:0xf bound_ctrl:1
	v_add_f32_dpp v199, v199, v199 row_half_mirror row_mask:0xf bank_mask:0xf bound_ctrl:1
	v_pk_fma_f32 v[8:9], v[8:9], v[124:125], v[188:189] op_sel:[0,1,0] op_sel_hi:[1,1,1]
	v_add_f32_dpp v198, v198, v198 row_mirror row_mask:0xf bank_mask:0xf bound_ctrl:1
	v_add_f32_dpp v199, v199, v199 row_mirror row_mask:0xf bank_mask:0xf bound_ctrl:1
	v_pk_fma_f32 v[2:3], v[126:127], v[198:199], v[2:3] op_sel:[0,0,0] op_sel_hi:[0,1,1] neg_lo:[0,1,0] neg_hi:[0,1,0]
	v_pk_fma_f32 v[4:5], v[126:127], v[198:199], v[4:5] op_sel:[1,0,0] op_sel_hi:[1,1,1] neg_lo:[0,1,0] neg_hi:[0,1,0]
	v_pk_mul_f32 v[10:11], v[2:3], v[138:139] op_sel:[0,0] op_sel_hi:[1,0]
	v_pk_fma_f32 v[6:7], v[128:129], v[198:199], v[6:7] op_sel:[0,0,0] op_sel_hi:[0,1,1] neg_lo:[0,1,0] neg_hi:[0,1,0]
	v_pk_fma_f32 v[10:11], v[4:5], v[138:139], v[10:11] op_sel:[0,1,0] op_sel_hi:[1,1,1]
	v_pk_fma_f32 v[8:9], v[128:129], v[198:199], v[8:9] op_sel:[1,0,0] op_sel_hi:[1,1,1] neg_lo:[0,1,0] neg_hi:[0,1,0]
	v_pk_fma_f32 v[10:11], v[6:7], v[140:141], v[10:11] op_sel:[0,0,0] op_sel_hi:[1,0,1]
	v_pk_fma_f32 v[10:11], v[8:9], v[140:141], v[10:11] op_sel:[0,1,0] op_sel_hi:[1,1,1]
	s_waitcnt lgkmcnt(0)
	ds_read_b128 v[134:137], v42 offset:3840
	ds_read_b128 v[130:133], v42 offset:3584
	ds_read_b64 v[142:143], v43 offset:3072
	ds_read_b128 v[122:125], v42 offset:3072
	ds_read_b128 v[126:129], v42 offset:3328
	ds_read_b128 v[138:141], v42 offset:4096
	v_pk_mul_f32 v[198:199], v[2:3], v[166:167] op_sel:[0,0] op_sel_hi:[1,0]
	v_pk_mul_f32 v[176:177], v[174:175], v[162:163] op_sel:[0,0] op_sel_hi:[1,0]
	v_pk_fma_f32 v[198:199], v[4:5], v[166:167], v[198:199] op_sel:[0,1,0] op_sel_hi:[1,1,1]
	v_pk_mul_f32 v[178:179], v[174:175], v[162:163] op_sel:[0,1] op_sel_hi:[1,1]
	v_pk_fma_f32 v[198:199], v[6:7], v[168:169], v[198:199] op_sel:[0,0,0] op_sel_hi:[1,0,1]
	v_pk_mul_f32 v[180:181], v[174:175], v[164:165] op_sel:[0,0] op_sel_hi:[1,0]
	v_pk_fma_f32 v[198:199], v[8:9], v[168:169], v[198:199] op_sel:[0,1,0] op_sel_hi:[1,1,1]
	v_pk_mul_f32 v[188:189], v[174:175], v[164:165] op_sel:[0,1] op_sel_hi:[1,1]
	v_pk_fma_f32 v[2:3], v[2:3], v[154:155], v[176:177] op_sel:[0,0,0] op_sel_hi:[1,0,1]
	v_add_f32_dpp v198, v198, v198 quad_perm:[1,0,3,2] row_mask:0xf bank_mask:0xf bound_ctrl:1
	v_add_f32_dpp v199, v199, v199 quad_perm:[1,0,3,2] row_mask:0xf bank_mask:0xf bound_ctrl:1
	v_pk_fma_f32 v[4:5], v[4:5], v[154:155], v[178:179] op_sel:[0,1,0] op_sel_hi:[1,1,1]
	v_add_f32_dpp v198, v198, v198 quad_perm:[2,3,0,1] row_mask:0xf bank_mask:0xf bound_ctrl:1
	v_add_f32_dpp v199, v199, v199 quad_perm:[2,3,0,1] row_mask:0xf bank_mask:0xf bound_ctrl:1
	v_pk_fma_f32 v[6:7], v[6:7], v[156:157], v[180:181] op_sel:[0,0,0] op_sel_hi:[1,0,1]
	v_add_f32_dpp v198, v198, v198 row_half_mirror row_mask:0xf bank_mask:0xf bound_ctrl:1
	v_add_f32_dpp v199, v199, v199 row_half_mirror row_mask:0xf bank_mask:0xf bound_ctrl:1
	v_pk_fma_f32 v[8:9], v[8:9], v[156:157], v[188:189] op_sel:[0,1,0] op_sel_hi:[1,1,1]
	v_add_f32_dpp v198, v198, v198 row_mirror row_mask:0xf bank_mask:0xf bound_ctrl:1
	v_add_f32_dpp v199, v199, v199 row_mirror row_mask:0xf bank_mask:0xf bound_ctrl:1
	v_pk_fma_f32 v[2:3], v[158:159], v[198:199], v[2:3] op_sel:[0,0,0] op_sel_hi:[0,1,1] neg_lo:[0,1,0] neg_hi:[0,1,0]
	v_pk_fma_f32 v[4:5], v[158:159], v[198:199], v[4:5] op_sel:[1,0,0] op_sel_hi:[1,1,1] neg_lo:[0,1,0] neg_hi:[0,1,0]
	v_pk_mul_f32 v[12:13], v[2:3], v[170:171] op_sel:[0,0] op_sel_hi:[1,0]
	v_pk_fma_f32 v[6:7], v[160:161], v[198:199], v[6:7] op_sel:[0,0,0] op_sel_hi:[0,1,1] neg_lo:[0,1,0] neg_hi:[0,1,0]
	v_pk_fma_f32 v[12:13], v[4:5], v[170:171], v[12:13] op_sel:[0,1,0] op_sel_hi:[1,1,1]
	v_pk_fma_f32 v[8:9], v[160:161], v[198:199], v[8:9] op_sel:[1,0,0] op_sel_hi:[1,1,1] neg_lo:[0,1,0] neg_hi:[0,1,0]
	v_pk_fma_f32 v[12:13], v[6:7], v[172:173], v[12:13] op_sel:[0,0,0] op_sel_hi:[1,0,1]
	v_pk_fma_f32 v[12:13], v[8:9], v[172:173], v[12:13] op_sel:[0,1,0] op_sel_hi:[1,1,1]
	s_waitcnt lgkmcnt(0)
	ds_read_b128 v[166:169], v42 offset:5376
	ds_read_b128 v[162:165], v42 offset:5120
	ds_read_b64 v[174:175], v43 offset:4608
	ds_read_b128 v[154:157], v42 offset:4608
	ds_read_b128 v[158:161], v42 offset:4864
	ds_read_b128 v[170:173], v42 offset:5632
	v_pk_mul_f32 v[198:199], v[2:3], v[134:135] op_sel:[0,0] op_sel_hi:[1,0]
	v_pk_mul_f32 v[176:177], v[142:143], v[130:131] op_sel:[0,0] op_sel_hi:[1,0]
	v_pk_fma_f32 v[198:199], v[4:5], v[134:135], v[198:199] op_sel:[0,1,0] op_sel_hi:[1,1,1]
	v_pk_mul_f32 v[178:179], v[142:143], v[130:131] op_sel:[0,1] op_sel_hi:[1,1]
	v_pk_fma_f32 v[198:199], v[6:7], v[136:137], v[198:199] op_sel:[0,0,0] op_sel_hi:[1,0,1]
	v_pk_mul_f32 v[180:181], v[142:143], v[132:133] op_sel:[0,0] op_sel_hi:[1,0]
	v_pk_fma_f32 v[198:199], v[8:9], v[136:137], v[198:199] op_sel:[0,1,0] op_sel_hi:[1,1,1]
	v_pk_mul_f32 v[188:189], v[142:143], v[132:133] op_sel:[0,1] op_sel_hi:[1,1]
	v_pk_fma_f32 v[2:3], v[2:3], v[122:123], v[176:177] op_sel:[0,0,0] op_sel_hi:[1,0,1]
	v_add_f32_dpp v198, v198, v198 quad_perm:[1,0,3,2] row_mask:0xf bank_mask:0xf bound_ctrl:1
	v_add_f32_dpp v199, v199, v199 quad_perm:[1,0,3,2] row_mask:0xf bank_mask:0xf bound_ctrl:1
	v_pk_fma_f32 v[4:5], v[4:5], v[122:123], v[178:179] op_sel:[0,1,0] op_sel_hi:[1,1,1]
	v_add_f32_dpp v198, v198, v198 quad_perm:[2,3,0,1] row_mask:0xf bank_mask:0xf bound_ctrl:1
	v_add_f32_dpp v199, v199, v199 quad_perm:[2,3,0,1] row_mask:0xf bank_mask:0xf bound_ctrl:1
	v_pk_fma_f32 v[6:7], v[6:7], v[124:125], v[180:181] op_sel:[0,0,0] op_sel_hi:[1,0,1]
	v_add_f32_dpp v198, v198, v198 row_half_mirror row_mask:0xf bank_mask:0xf bound_ctrl:1
	v_add_f32_dpp v199, v199, v199 row_half_mirror row_mask:0xf bank_mask:0xf bound_ctrl:1
	v_pk_fma_f32 v[8:9], v[8:9], v[124:125], v[188:189] op_sel:[0,1,0] op_sel_hi:[1,1,1]
	v_add_f32_dpp v198, v198, v198 row_mirror row_mask:0xf bank_mask:0xf bound_ctrl:1
	v_add_f32_dpp v199, v199, v199 row_mirror row_mask:0xf bank_mask:0xf bound_ctrl:1
	v_pk_fma_f32 v[2:3], v[126:127], v[198:199], v[2:3] op_sel:[0,0,0] op_sel_hi:[0,1,1] neg_lo:[0,1,0] neg_hi:[0,1,0]
	v_pk_fma_f32 v[4:5], v[126:127], v[198:199], v[4:5] op_sel:[1,0,0] op_sel_hi:[1,1,1] neg_lo:[0,1,0] neg_hi:[0,1,0]
	v_pk_mul_f32 v[14:15], v[2:3], v[138:139] op_sel:[0,0] op_sel_hi:[1,0]
	v_pk_fma_f32 v[6:7], v[128:129], v[198:199], v[6:7] op_sel:[0,0,0] op_sel_hi:[0,1,1] neg_lo:[0,1,0] neg_hi:[0,1,0]
	v_pk_fma_f32 v[14:15], v[4:5], v[138:139], v[14:15] op_sel:[0,1,0] op_sel_hi:[1,1,1]
	v_pk_fma_f32 v[8:9], v[128:129], v[198:199], v[8:9] op_sel:[1,0,0] op_sel_hi:[1,1,1] neg_lo:[0,1,0] neg_hi:[0,1,0]
	v_pk_fma_f32 v[14:15], v[6:7], v[140:141], v[14:15] op_sel:[0,0,0] op_sel_hi:[1,0,1]
	v_pk_fma_f32 v[14:15], v[8:9], v[140:141], v[14:15] op_sel:[0,1,0] op_sel_hi:[1,1,1]
	s_waitcnt lgkmcnt(0)
	ds_read_b128 v[134:137], v42 offset:6912
	ds_read_b128 v[130:133], v42 offset:6656
	ds_read_b64 v[142:143], v43 offset:6144
	ds_read_b128 v[122:125], v42 offset:6144
	ds_read_b128 v[126:129], v42 offset:6400
	ds_read_b128 v[138:141], v42 offset:7168
	v_pk_mul_f32 v[198:199], v[2:3], v[166:167] op_sel:[0,0] op_sel_hi:[1,0]
	v_pk_mul_f32 v[176:177], v[174:175], v[162:163] op_sel:[0,0] op_sel_hi:[1,0]
	v_pk_fma_f32 v[198:199], v[4:5], v[166:167], v[198:199] op_sel:[0,1,0] op_sel_hi:[1,1,1]
	v_pk_mul_f32 v[178:179], v[174:175], v[162:163] op_sel:[0,1] op_sel_hi:[1,1]
	v_pk_fma_f32 v[198:199], v[6:7], v[168:169], v[198:199] op_sel:[0,0,0] op_sel_hi:[1,0,1]
	v_pk_mul_f32 v[180:181], v[174:175], v[164:165] op_sel:[0,0] op_sel_hi:[1,0]
	v_pk_fma_f32 v[198:199], v[8:9], v[168:169], v[198:199] op_sel:[0,1,0] op_sel_hi:[1,1,1]
	v_pk_mul_f32 v[188:189], v[174:175], v[164:165] op_sel:[0,1] op_sel_hi:[1,1]
	v_pk_fma_f32 v[2:3], v[2:3], v[154:155], v[176:177] op_sel:[0,0,0] op_sel_hi:[1,0,1]
	v_add_f32_dpp v198, v198, v198 quad_perm:[1,0,3,2] row_mask:0xf bank_mask:0xf bound_ctrl:1
	v_add_f32_dpp v199, v199, v199 quad_perm:[1,0,3,2] row_mask:0xf bank_mask:0xf bound_ctrl:1
	v_pk_fma_f32 v[4:5], v[4:5], v[154:155], v[178:179] op_sel:[0,1,0] op_sel_hi:[1,1,1]
	v_add_f32_dpp v198, v198, v198 quad_perm:[2,3,0,1] row_mask:0xf bank_mask:0xf bound_ctrl:1
	v_add_f32_dpp v199, v199, v199 quad_perm:[2,3,0,1] row_mask:0xf bank_mask:0xf bound_ctrl:1
	v_pk_fma_f32 v[6:7], v[6:7], v[156:157], v[180:181] op_sel:[0,0,0] op_sel_hi:[1,0,1]
	v_add_f32_dpp v198, v198, v198 row_half_mirror row_mask:0xf bank_mask:0xf bound_ctrl:1
	v_add_f32_dpp v199, v199, v199 row_half_mirror row_mask:0xf bank_mask:0xf bound_ctrl:1
	v_pk_fma_f32 v[8:9], v[8:9], v[156:157], v[188:189] op_sel:[0,1,0] op_sel_hi:[1,1,1]
	v_add_f32_dpp v198, v198, v198 row_mirror row_mask:0xf bank_mask:0xf bound_ctrl:1
	v_add_f32_dpp v199, v199, v199 row_mirror row_mask:0xf bank_mask:0xf bound_ctrl:1
	v_pk_fma_f32 v[2:3], v[158:159], v[198:199], v[2:3] op_sel:[0,0,0] op_sel_hi:[0,1,1] neg_lo:[0,1,0] neg_hi:[0,1,0]
	v_pk_fma_f32 v[4:5], v[158:159], v[198:199], v[4:5] op_sel:[1,0,0] op_sel_hi:[1,1,1] neg_lo:[0,1,0] neg_hi:[0,1,0]
	v_pk_mul_f32 v[16:17], v[2:3], v[170:171] op_sel:[0,0] op_sel_hi:[1,0]
	v_pk_fma_f32 v[6:7], v[160:161], v[198:199], v[6:7] op_sel:[0,0,0] op_sel_hi:[0,1,1] neg_lo:[0,1,0] neg_hi:[0,1,0]
	v_pk_fma_f32 v[16:17], v[4:5], v[170:171], v[16:17] op_sel:[0,1,0] op_sel_hi:[1,1,1]
	v_pk_fma_f32 v[8:9], v[160:161], v[198:199], v[8:9] op_sel:[1,0,0] op_sel_hi:[1,1,1] neg_lo:[0,1,0] neg_hi:[0,1,0]
	v_pk_fma_f32 v[16:17], v[6:7], v[172:173], v[16:17] op_sel:[0,0,0] op_sel_hi:[1,0,1]
	v_pk_fma_f32 v[16:17], v[8:9], v[172:173], v[16:17] op_sel:[0,1,0] op_sel_hi:[1,1,1]
	s_waitcnt lgkmcnt(0)
	ds_read_b128 v[166:169], v42 offset:8448
	ds_read_b128 v[162:165], v42 offset:8192
	ds_read_b64 v[174:175], v43 offset:7680
	ds_read_b128 v[154:157], v42 offset:7680
	ds_read_b128 v[158:161], v42 offset:7936
	ds_read_b128 v[170:173], v42 offset:8704
	v_pk_mul_f32 v[198:199], v[2:3], v[134:135] op_sel:[0,0] op_sel_hi:[1,0]
	v_pk_mul_f32 v[176:177], v[142:143], v[130:131] op_sel:[0,0] op_sel_hi:[1,0]
	v_pk_fma_f32 v[198:199], v[4:5], v[134:135], v[198:199] op_sel:[0,1,0] op_sel_hi:[1,1,1]
	v_pk_mul_f32 v[178:179], v[142:143], v[130:131] op_sel:[0,1] op_sel_hi:[1,1]
	v_pk_fma_f32 v[198:199], v[6:7], v[136:137], v[198:199] op_sel:[0,0,0] op_sel_hi:[1,0,1]
	v_pk_mul_f32 v[180:181], v[142:143], v[132:133] op_sel:[0,0] op_sel_hi:[1,0]
	v_pk_fma_f32 v[198:199], v[8:9], v[136:137], v[198:199] op_sel:[0,1,0] op_sel_hi:[1,1,1]
	v_pk_mul_f32 v[188:189], v[142:143], v[132:133] op_sel:[0,1] op_sel_hi:[1,1]
	v_pk_fma_f32 v[2:3], v[2:3], v[122:123], v[176:177] op_sel:[0,0,0] op_sel_hi:[1,0,1]
	v_add_f32_dpp v198, v198, v198 quad_perm:[1,0,3,2] row_mask:0xf bank_mask:0xf bound_ctrl:1
	v_add_f32_dpp v199, v199, v199 quad_perm:[1,0,3,2] row_mask:0xf bank_mask:0xf bound_ctrl:1
	v_pk_fma_f32 v[4:5], v[4:5], v[122:123], v[178:179] op_sel:[0,1,0] op_sel_hi:[1,1,1]
	v_add_f32_dpp v198, v198, v198 quad_perm:[2,3,0,1] row_mask:0xf bank_mask:0xf bound_ctrl:1
	v_add_f32_dpp v199, v199, v199 quad_perm:[2,3,0,1] row_mask:0xf bank_mask:0xf bound_ctrl:1
	v_pk_fma_f32 v[6:7], v[6:7], v[124:125], v[180:181] op_sel:[0,0,0] op_sel_hi:[1,0,1]
	v_add_f32_dpp v198, v198, v198 row_half_mirror row_mask:0xf bank_mask:0xf bound_ctrl:1
	v_add_f32_dpp v199, v199, v199 row_half_mirror row_mask:0xf bank_mask:0xf bound_ctrl:1
	v_pk_fma_f32 v[8:9], v[8:9], v[124:125], v[188:189] op_sel:[0,1,0] op_sel_hi:[1,1,1]
	v_add_f32_dpp v198, v198, v198 row_mirror row_mask:0xf bank_mask:0xf bound_ctrl:1
	v_add_f32_dpp v199, v199, v199 row_mirror row_mask:0xf bank_mask:0xf bound_ctrl:1
	v_pk_fma_f32 v[2:3], v[126:127], v[198:199], v[2:3] op_sel:[0,0,0] op_sel_hi:[0,1,1] neg_lo:[0,1,0] neg_hi:[0,1,0]
	v_pk_fma_f32 v[4:5], v[126:127], v[198:199], v[4:5] op_sel:[1,0,0] op_sel_hi:[1,1,1] neg_lo:[0,1,0] neg_hi:[0,1,0]
	v_pk_mul_f32 v[18:19], v[2:3], v[138:139] op_sel:[0,0] op_sel_hi:[1,0]
	v_pk_fma_f32 v[6:7], v[128:129], v[198:199], v[6:7] op_sel:[0,0,0] op_sel_hi:[0,1,1] neg_lo:[0,1,0] neg_hi:[0,1,0]
	v_pk_fma_f32 v[18:19], v[4:5], v[138:139], v[18:19] op_sel:[0,1,0] op_sel_hi:[1,1,1]
	v_pk_fma_f32 v[8:9], v[128:129], v[198:199], v[8:9] op_sel:[1,0,0] op_sel_hi:[1,1,1] neg_lo:[0,1,0] neg_hi:[0,1,0]
	v_pk_fma_f32 v[18:19], v[6:7], v[140:141], v[18:19] op_sel:[0,0,0] op_sel_hi:[1,0,1]
	v_pk_fma_f32 v[18:19], v[8:9], v[140:141], v[18:19] op_sel:[0,1,0] op_sel_hi:[1,1,1]
	s_waitcnt lgkmcnt(0)
	ds_read_b128 v[134:137], v42 offset:9984
	ds_read_b128 v[130:133], v42 offset:9728
	ds_read_b64 v[142:143], v43 offset:9216
	ds_read_b128 v[122:125], v42 offset:9216
	ds_read_b128 v[126:129], v42 offset:9472
	ds_read_b128 v[138:141], v42 offset:10240
	v_pk_mul_f32 v[198:199], v[2:3], v[166:167] op_sel:[0,0] op_sel_hi:[1,0]
	v_pk_mul_f32 v[176:177], v[174:175], v[162:163] op_sel:[0,0] op_sel_hi:[1,0]
	v_pk_fma_f32 v[198:199], v[4:5], v[166:167], v[198:199] op_sel:[0,1,0] op_sel_hi:[1,1,1]
	v_pk_mul_f32 v[178:179], v[174:175], v[162:163] op_sel:[0,1] op_sel_hi:[1,1]
	v_pk_fma_f32 v[198:199], v[6:7], v[168:169], v[198:199] op_sel:[0,0,0] op_sel_hi:[1,0,1]
	v_pk_mul_f32 v[180:181], v[174:175], v[164:165] op_sel:[0,0] op_sel_hi:[1,0]
	v_pk_fma_f32 v[198:199], v[8:9], v[168:169], v[198:199] op_sel:[0,1,0] op_sel_hi:[1,1,1]
	v_pk_mul_f32 v[188:189], v[174:175], v[164:165] op_sel:[0,1] op_sel_hi:[1,1]
	v_pk_fma_f32 v[2:3], v[2:3], v[154:155], v[176:177] op_sel:[0,0,0] op_sel_hi:[1,0,1]
	v_add_f32_dpp v198, v198, v198 quad_perm:[1,0,3,2] row_mask:0xf bank_mask:0xf bound_ctrl:1
	v_add_f32_dpp v199, v199, v199 quad_perm:[1,0,3,2] row_mask:0xf bank_mask:0xf bound_ctrl:1
	v_pk_fma_f32 v[4:5], v[4:5], v[154:155], v[178:179] op_sel:[0,1,0] op_sel_hi:[1,1,1]
	v_add_f32_dpp v198, v198, v198 quad_perm:[2,3,0,1] row_mask:0xf bank_mask:0xf bound_ctrl:1
	v_add_f32_dpp v199, v199, v199 quad_perm:[2,3,0,1] row_mask:0xf bank_mask:0xf bound_ctrl:1
	v_pk_fma_f32 v[6:7], v[6:7], v[156:157], v[180:181] op_sel:[0,0,0] op_sel_hi:[1,0,1]
	v_add_f32_dpp v198, v198, v198 row_half_mirror row_mask:0xf bank_mask:0xf bound_ctrl:1
	v_add_f32_dpp v199, v199, v199 row_half_mirror row_mask:0xf bank_mask:0xf bound_ctrl:1
	v_pk_fma_f32 v[8:9], v[8:9], v[156:157], v[188:189] op_sel:[0,1,0] op_sel_hi:[1,1,1]
	v_add_f32_dpp v198, v198, v198 row_mirror row_mask:0xf bank_mask:0xf bound_ctrl:1
	v_add_f32_dpp v199, v199, v199 row_mirror row_mask:0xf bank_mask:0xf bound_ctrl:1
	v_pk_fma_f32 v[2:3], v[158:159], v[198:199], v[2:3] op_sel:[0,0,0] op_sel_hi:[0,1,1] neg_lo:[0,1,0] neg_hi:[0,1,0]
	v_pk_fma_f32 v[4:5], v[158:159], v[198:199], v[4:5] op_sel:[1,0,0] op_sel_hi:[1,1,1] neg_lo:[0,1,0] neg_hi:[0,1,0]
	v_pk_mul_f32 v[20:21], v[2:3], v[170:171] op_sel:[0,0] op_sel_hi:[1,0]
	v_pk_fma_f32 v[6:7], v[160:161], v[198:199], v[6:7] op_sel:[0,0,0] op_sel_hi:[0,1,1] neg_lo:[0,1,0] neg_hi:[0,1,0]
	v_pk_fma_f32 v[20:21], v[4:5], v[170:171], v[20:21] op_sel:[0,1,0] op_sel_hi:[1,1,1]
	v_pk_fma_f32 v[8:9], v[160:161], v[198:199], v[8:9] op_sel:[1,0,0] op_sel_hi:[1,1,1] neg_lo:[0,1,0] neg_hi:[0,1,0]
	v_pk_fma_f32 v[20:21], v[6:7], v[172:173], v[20:21] op_sel:[0,0,0] op_sel_hi:[1,0,1]
	v_pk_fma_f32 v[20:21], v[8:9], v[172:173], v[20:21] op_sel:[0,1,0] op_sel_hi:[1,1,1]
	s_waitcnt lgkmcnt(0)
	ds_read_b128 v[166:169], v42 offset:11520
	ds_read_b128 v[162:165], v42 offset:11264
	ds_read_b64 v[174:175], v43 offset:10752
	ds_read_b128 v[154:157], v42 offset:10752
	ds_read_b128 v[158:161], v42 offset:11008
	ds_read_b128 v[170:173], v42 offset:11776
	v_pk_mul_f32 v[198:199], v[2:3], v[134:135] op_sel:[0,0] op_sel_hi:[1,0]
	v_pk_mul_f32 v[176:177], v[142:143], v[130:131] op_sel:[0,0] op_sel_hi:[1,0]
	v_pk_fma_f32 v[198:199], v[4:5], v[134:135], v[198:199] op_sel:[0,1,0] op_sel_hi:[1,1,1]
	v_pk_mul_f32 v[178:179], v[142:143], v[130:131] op_sel:[0,1] op_sel_hi:[1,1]
	v_pk_fma_f32 v[198:199], v[6:7], v[136:137], v[198:199] op_sel:[0,0,0] op_sel_hi:[1,0,1]
	v_pk_mul_f32 v[180:181], v[142:143], v[132:133] op_sel:[0,0] op_sel_hi:[1,0]
	v_pk_fma_f32 v[198:199], v[8:9], v[136:137], v[198:199] op_sel:[0,1,0] op_sel_hi:[1,1,1]
	v_pk_mul_f32 v[188:189], v[142:143], v[132:133] op_sel:[0,1] op_sel_hi:[1,1]
	v_pk_fma_f32 v[2:3], v[2:3], v[122:123], v[176:177] op_sel:[0,0,0] op_sel_hi:[1,0,1]
	v_add_f32_dpp v198, v198, v198 quad_perm:[1,0,3,2] row_mask:0xf bank_mask:0xf bound_ctrl:1
	v_add_f32_dpp v199, v199, v199 quad_perm:[1,0,3,2] row_mask:0xf bank_mask:0xf bound_ctrl:1
	v_pk_fma_f32 v[4:5], v[4:5], v[122:123], v[178:179] op_sel:[0,1,0] op_sel_hi:[1,1,1]
	v_add_f32_dpp v198, v198, v198 quad_perm:[2,3,0,1] row_mask:0xf bank_mask:0xf bound_ctrl:1
	v_add_f32_dpp v199, v199, v199 quad_perm:[2,3,0,1] row_mask:0xf bank_mask:0xf bound_ctrl:1
	v_pk_fma_f32 v[6:7], v[6:7], v[124:125], v[180:181] op_sel:[0,0,0] op_sel_hi:[1,0,1]
	v_add_f32_dpp v198, v198, v198 row_half_mirror row_mask:0xf bank_mask:0xf bound_ctrl:1
	v_add_f32_dpp v199, v199, v199 row_half_mirror row_mask:0xf bank_mask:0xf bound_ctrl:1
	v_pk_fma_f32 v[8:9], v[8:9], v[124:125], v[188:189] op_sel:[0,1,0] op_sel_hi:[1,1,1]
	v_add_f32_dpp v198, v198, v198 row_mirror row_mask:0xf bank_mask:0xf bound_ctrl:1
	v_add_f32_dpp v199, v199, v199 row_mirror row_mask:0xf bank_mask:0xf bound_ctrl:1
	v_pk_fma_f32 v[2:3], v[126:127], v[198:199], v[2:3] op_sel:[0,0,0] op_sel_hi:[0,1,1] neg_lo:[0,1,0] neg_hi:[0,1,0]
	v_pk_fma_f32 v[4:5], v[126:127], v[198:199], v[4:5] op_sel:[1,0,0] op_sel_hi:[1,1,1] neg_lo:[0,1,0] neg_hi:[0,1,0]
	v_pk_mul_f32 v[22:23], v[2:3], v[138:139] op_sel:[0,0] op_sel_hi:[1,0]
	v_pk_fma_f32 v[6:7], v[128:129], v[198:199], v[6:7] op_sel:[0,0,0] op_sel_hi:[0,1,1] neg_lo:[0,1,0] neg_hi:[0,1,0]
	v_pk_fma_f32 v[22:23], v[4:5], v[138:139], v[22:23] op_sel:[0,1,0] op_sel_hi:[1,1,1]
	v_pk_fma_f32 v[8:9], v[128:129], v[198:199], v[8:9] op_sel:[1,0,0] op_sel_hi:[1,1,1] neg_lo:[0,1,0] neg_hi:[0,1,0]
	v_pk_fma_f32 v[22:23], v[6:7], v[140:141], v[22:23] op_sel:[0,0,0] op_sel_hi:[1,0,1]
	v_pk_fma_f32 v[22:23], v[8:9], v[140:141], v[22:23] op_sel:[0,1,0] op_sel_hi:[1,1,1]
	s_waitcnt lgkmcnt(0)
	ds_read_b128 v[134:137], v42 offset:13056
	ds_read_b128 v[130:133], v42 offset:12800
	ds_read_b64 v[142:143], v43 offset:12288
	ds_read_b128 v[122:125], v42 offset:12288
	ds_read_b128 v[126:129], v42 offset:12544
	ds_read_b128 v[138:141], v42 offset:13312
	v_pk_mul_f32 v[198:199], v[2:3], v[166:167] op_sel:[0,0] op_sel_hi:[1,0]
	v_pk_mul_f32 v[176:177], v[174:175], v[162:163] op_sel:[0,0] op_sel_hi:[1,0]
	v_pk_fma_f32 v[198:199], v[4:5], v[166:167], v[198:199] op_sel:[0,1,0] op_sel_hi:[1,1,1]
	v_pk_mul_f32 v[178:179], v[174:175], v[162:163] op_sel:[0,1] op_sel_hi:[1,1]
	v_pk_fma_f32 v[198:199], v[6:7], v[168:169], v[198:199] op_sel:[0,0,0] op_sel_hi:[1,0,1]
	v_pk_mul_f32 v[180:181], v[174:175], v[164:165] op_sel:[0,0] op_sel_hi:[1,0]
	v_pk_fma_f32 v[198:199], v[8:9], v[168:169], v[198:199] op_sel:[0,1,0] op_sel_hi:[1,1,1]
	v_pk_mul_f32 v[188:189], v[174:175], v[164:165] op_sel:[0,1] op_sel_hi:[1,1]
	v_pk_fma_f32 v[2:3], v[2:3], v[154:155], v[176:177] op_sel:[0,0,0] op_sel_hi:[1,0,1]
	v_add_f32_dpp v198, v198, v198 quad_perm:[1,0,3,2] row_mask:0xf bank_mask:0xf bound_ctrl:1
	v_add_f32_dpp v199, v199, v199 quad_perm:[1,0,3,2] row_mask:0xf bank_mask:0xf bound_ctrl:1
	v_pk_fma_f32 v[4:5], v[4:5], v[154:155], v[178:179] op_sel:[0,1,0] op_sel_hi:[1,1,1]
	v_add_f32_dpp v198, v198, v198 quad_perm:[2,3,0,1] row_mask:0xf bank_mask:0xf bound_ctrl:1
	v_add_f32_dpp v199, v199, v199 quad_perm:[2,3,0,1] row_mask:0xf bank_mask:0xf bound_ctrl:1
	v_pk_fma_f32 v[6:7], v[6:7], v[156:157], v[180:181] op_sel:[0,0,0] op_sel_hi:[1,0,1]
	v_add_f32_dpp v198, v198, v198 row_half_mirror row_mask:0xf bank_mask:0xf bound_ctrl:1
	v_add_f32_dpp v199, v199, v199 row_half_mirror row_mask:0xf bank_mask:0xf bound_ctrl:1
	v_pk_fma_f32 v[8:9], v[8:9], v[156:157], v[188:189] op_sel:[0,1,0] op_sel_hi:[1,1,1]
	v_add_f32_dpp v198, v198, v198 row_mirror row_mask:0xf bank_mask:0xf bound_ctrl:1
	v_add_f32_dpp v199, v199, v199 row_mirror row_mask:0xf bank_mask:0xf bound_ctrl:1
	v_pk_fma_f32 v[2:3], v[158:159], v[198:199], v[2:3] op_sel:[0,0,0] op_sel_hi:[0,1,1] neg_lo:[0,1,0] neg_hi:[0,1,0]
	v_pk_fma_f32 v[4:5], v[158:159], v[198:199], v[4:5] op_sel:[1,0,0] op_sel_hi:[1,1,1] neg_lo:[0,1,0] neg_hi:[0,1,0]
	v_pk_mul_f32 v[24:25], v[2:3], v[170:171] op_sel:[0,0] op_sel_hi:[1,0]
	v_pk_fma_f32 v[6:7], v[160:161], v[198:199], v[6:7] op_sel:[0,0,0] op_sel_hi:[0,1,1] neg_lo:[0,1,0] neg_hi:[0,1,0]
	v_pk_fma_f32 v[24:25], v[4:5], v[170:171], v[24:25] op_sel:[0,1,0] op_sel_hi:[1,1,1]
	v_pk_fma_f32 v[8:9], v[160:161], v[198:199], v[8:9] op_sel:[1,0,0] op_sel_hi:[1,1,1] neg_lo:[0,1,0] neg_hi:[0,1,0]
	v_pk_fma_f32 v[24:25], v[6:7], v[172:173], v[24:25] op_sel:[0,0,0] op_sel_hi:[1,0,1]
	v_pk_fma_f32 v[24:25], v[8:9], v[172:173], v[24:25] op_sel:[0,1,0] op_sel_hi:[1,1,1]
	s_waitcnt lgkmcnt(0)
	ds_read_b128 v[166:169], v42 offset:14592
	ds_read_b128 v[162:165], v42 offset:14336
	ds_read_b64 v[174:175], v43 offset:13824
	ds_read_b128 v[154:157], v42 offset:13824
	ds_read_b128 v[158:161], v42 offset:14080
	ds_read_b128 v[170:173], v42 offset:14848
	v_pk_mul_f32 v[198:199], v[2:3], v[134:135] op_sel:[0,0] op_sel_hi:[1,0]
	v_pk_mul_f32 v[176:177], v[142:143], v[130:131] op_sel:[0,0] op_sel_hi:[1,0]
	v_pk_fma_f32 v[198:199], v[4:5], v[134:135], v[198:199] op_sel:[0,1,0] op_sel_hi:[1,1,1]
	v_pk_mul_f32 v[178:179], v[142:143], v[130:131] op_sel:[0,1] op_sel_hi:[1,1]
	v_pk_fma_f32 v[198:199], v[6:7], v[136:137], v[198:199] op_sel:[0,0,0] op_sel_hi:[1,0,1]
	v_pk_mul_f32 v[180:181], v[142:143], v[132:133] op_sel:[0,0] op_sel_hi:[1,0]
	v_pk_fma_f32 v[198:199], v[8:9], v[136:137], v[198:199] op_sel:[0,1,0] op_sel_hi:[1,1,1]
	v_pk_mul_f32 v[188:189], v[142:143], v[132:133] op_sel:[0,1] op_sel_hi:[1,1]
	v_pk_fma_f32 v[2:3], v[2:3], v[122:123], v[176:177] op_sel:[0,0,0] op_sel_hi:[1,0,1]
	v_add_f32_dpp v198, v198, v198 quad_perm:[1,0,3,2] row_mask:0xf bank_mask:0xf bound_ctrl:1
	v_add_f32_dpp v199, v199, v199 quad_perm:[1,0,3,2] row_mask:0xf bank_mask:0xf bound_ctrl:1
	v_pk_fma_f32 v[4:5], v[4:5], v[122:123], v[178:179] op_sel:[0,1,0] op_sel_hi:[1,1,1]
	v_add_f32_dpp v198, v198, v198 quad_perm:[2,3,0,1] row_mask:0xf bank_mask:0xf bound_ctrl:1
	v_add_f32_dpp v199, v199, v199 quad_perm:[2,3,0,1] row_mask:0xf bank_mask:0xf bound_ctrl:1
	v_pk_fma_f32 v[6:7], v[6:7], v[124:125], v[180:181] op_sel:[0,0,0] op_sel_hi:[1,0,1]
	v_add_f32_dpp v198, v198, v198 row_half_mirror row_mask:0xf bank_mask:0xf bound_ctrl:1
	v_add_f32_dpp v199, v199, v199 row_half_mirror row_mask:0xf bank_mask:0xf bound_ctrl:1
	v_pk_fma_f32 v[8:9], v[8:9], v[124:125], v[188:189] op_sel:[0,1,0] op_sel_hi:[1,1,1]
	v_add_f32_dpp v198, v198, v198 row_mirror row_mask:0xf bank_mask:0xf bound_ctrl:1
	v_add_f32_dpp v199, v199, v199 row_mirror row_mask:0xf bank_mask:0xf bound_ctrl:1
	v_pk_fma_f32 v[2:3], v[126:127], v[198:199], v[2:3] op_sel:[0,0,0] op_sel_hi:[0,1,1] neg_lo:[0,1,0] neg_hi:[0,1,0]
	v_pk_fma_f32 v[4:5], v[126:127], v[198:199], v[4:5] op_sel:[1,0,0] op_sel_hi:[1,1,1] neg_lo:[0,1,0] neg_hi:[0,1,0]
	v_pk_mul_f32 v[26:27], v[2:3], v[138:139] op_sel:[0,0] op_sel_hi:[1,0]
	v_pk_fma_f32 v[6:7], v[128:129], v[198:199], v[6:7] op_sel:[0,0,0] op_sel_hi:[0,1,1] neg_lo:[0,1,0] neg_hi:[0,1,0]
	v_pk_fma_f32 v[26:27], v[4:5], v[138:139], v[26:27] op_sel:[0,1,0] op_sel_hi:[1,1,1]
	v_pk_fma_f32 v[8:9], v[128:129], v[198:199], v[8:9] op_sel:[1,0,0] op_sel_hi:[1,1,1] neg_lo:[0,1,0] neg_hi:[0,1,0]
	v_pk_fma_f32 v[26:27], v[6:7], v[140:141], v[26:27] op_sel:[0,0,0] op_sel_hi:[1,0,1]
	v_pk_fma_f32 v[26:27], v[8:9], v[140:141], v[26:27] op_sel:[0,1,0] op_sel_hi:[1,1,1]
	s_waitcnt lgkmcnt(0)
	ds_read_b128 v[134:137], v42 offset:16128
	ds_read_b128 v[130:133], v42 offset:15872
	ds_read_b64 v[142:143], v43 offset:15360
	ds_read_b128 v[122:125], v42 offset:15360
	ds_read_b128 v[126:129], v42 offset:15616
	ds_read_b128 v[138:141], v42 offset:16384
	v_pk_mul_f32 v[198:199], v[2:3], v[166:167] op_sel:[0,0] op_sel_hi:[1,0]
	v_pk_mul_f32 v[176:177], v[174:175], v[162:163] op_sel:[0,0] op_sel_hi:[1,0]
	v_pk_fma_f32 v[198:199], v[4:5], v[166:167], v[198:199] op_sel:[0,1,0] op_sel_hi:[1,1,1]
	v_pk_mul_f32 v[178:179], v[174:175], v[162:163] op_sel:[0,1] op_sel_hi:[1,1]
	v_pk_fma_f32 v[198:199], v[6:7], v[168:169], v[198:199] op_sel:[0,0,0] op_sel_hi:[1,0,1]
	v_pk_mul_f32 v[180:181], v[174:175], v[164:165] op_sel:[0,0] op_sel_hi:[1,0]
	v_pk_fma_f32 v[198:199], v[8:9], v[168:169], v[198:199] op_sel:[0,1,0] op_sel_hi:[1,1,1]
	v_pk_mul_f32 v[188:189], v[174:175], v[164:165] op_sel:[0,1] op_sel_hi:[1,1]
	v_pk_fma_f32 v[2:3], v[2:3], v[154:155], v[176:177] op_sel:[0,0,0] op_sel_hi:[1,0,1]
	v_add_f32_dpp v198, v198, v198 quad_perm:[1,0,3,2] row_mask:0xf bank_mask:0xf bound_ctrl:1
	v_add_f32_dpp v199, v199, v199 quad_perm:[1,0,3,2] row_mask:0xf bank_mask:0xf bound_ctrl:1
	v_pk_fma_f32 v[4:5], v[4:5], v[154:155], v[178:179] op_sel:[0,1,0] op_sel_hi:[1,1,1]
	v_add_f32_dpp v198, v198, v198 quad_perm:[2,3,0,1] row_mask:0xf bank_mask:0xf bound_ctrl:1
	v_add_f32_dpp v199, v199, v199 quad_perm:[2,3,0,1] row_mask:0xf bank_mask:0xf bound_ctrl:1
	v_pk_fma_f32 v[6:7], v[6:7], v[156:157], v[180:181] op_sel:[0,0,0] op_sel_hi:[1,0,1]
	v_add_f32_dpp v198, v198, v198 row_half_mirror row_mask:0xf bank_mask:0xf bound_ctrl:1
	v_add_f32_dpp v199, v199, v199 row_half_mirror row_mask:0xf bank_mask:0xf bound_ctrl:1
	v_pk_fma_f32 v[8:9], v[8:9], v[156:157], v[188:189] op_sel:[0,1,0] op_sel_hi:[1,1,1]
	v_add_f32_dpp v198, v198, v198 row_mirror row_mask:0xf bank_mask:0xf bound_ctrl:1
	v_add_f32_dpp v199, v199, v199 row_mirror row_mask:0xf bank_mask:0xf bound_ctrl:1
	v_pk_fma_f32 v[2:3], v[158:159], v[198:199], v[2:3] op_sel:[0,0,0] op_sel_hi:[0,1,1] neg_lo:[0,1,0] neg_hi:[0,1,0]
	v_pk_fma_f32 v[4:5], v[158:159], v[198:199], v[4:5] op_sel:[1,0,0] op_sel_hi:[1,1,1] neg_lo:[0,1,0] neg_hi:[0,1,0]
	v_pk_mul_f32 v[28:29], v[2:3], v[170:171] op_sel:[0,0] op_sel_hi:[1,0]
	v_pk_fma_f32 v[6:7], v[160:161], v[198:199], v[6:7] op_sel:[0,0,0] op_sel_hi:[0,1,1] neg_lo:[0,1,0] neg_hi:[0,1,0]
	v_pk_fma_f32 v[28:29], v[4:5], v[170:171], v[28:29] op_sel:[0,1,0] op_sel_hi:[1,1,1]
	v_pk_fma_f32 v[8:9], v[160:161], v[198:199], v[8:9] op_sel:[1,0,0] op_sel_hi:[1,1,1] neg_lo:[0,1,0] neg_hi:[0,1,0]
	v_pk_fma_f32 v[28:29], v[6:7], v[172:173], v[28:29] op_sel:[0,0,0] op_sel_hi:[1,0,1]
	v_pk_fma_f32 v[28:29], v[8:9], v[172:173], v[28:29] op_sel:[0,1,0] op_sel_hi:[1,1,1]
	s_waitcnt lgkmcnt(0)
	ds_read_b128 v[166:169], v42 offset:17664
	ds_read_b128 v[162:165], v42 offset:17408
	ds_read_b64 v[174:175], v43 offset:16896
	ds_read_b128 v[154:157], v42 offset:16896
	ds_read_b128 v[158:161], v42 offset:17152
	ds_read_b128 v[170:173], v42 offset:17920
	v_pk_mul_f32 v[198:199], v[2:3], v[134:135] op_sel:[0,0] op_sel_hi:[1,0]
	v_pk_mul_f32 v[176:177], v[142:143], v[130:131] op_sel:[0,0] op_sel_hi:[1,0]
	v_pk_fma_f32 v[198:199], v[4:5], v[134:135], v[198:199] op_sel:[0,1,0] op_sel_hi:[1,1,1]
	v_pk_mul_f32 v[178:179], v[142:143], v[130:131] op_sel:[0,1] op_sel_hi:[1,1]
	v_pk_fma_f32 v[198:199], v[6:7], v[136:137], v[198:199] op_sel:[0,0,0] op_sel_hi:[1,0,1]
	v_pk_mul_f32 v[180:181], v[142:143], v[132:133] op_sel:[0,0] op_sel_hi:[1,0]
	v_pk_fma_f32 v[198:199], v[8:9], v[136:137], v[198:199] op_sel:[0,1,0] op_sel_hi:[1,1,1]
	v_pk_mul_f32 v[188:189], v[142:143], v[132:133] op_sel:[0,1] op_sel_hi:[1,1]
	v_pk_fma_f32 v[2:3], v[2:3], v[122:123], v[176:177] op_sel:[0,0,0] op_sel_hi:[1,0,1]
	v_add_f32_dpp v198, v198, v198 quad_perm:[1,0,3,2] row_mask:0xf bank_mask:0xf bound_ctrl:1
	v_add_f32_dpp v199, v199, v199 quad_perm:[1,0,3,2] row_mask:0xf bank_mask:0xf bound_ctrl:1
	v_pk_fma_f32 v[4:5], v[4:5], v[122:123], v[178:179] op_sel:[0,1,0] op_sel_hi:[1,1,1]
	v_add_f32_dpp v198, v198, v198 quad_perm:[2,3,0,1] row_mask:0xf bank_mask:0xf bound_ctrl:1
	v_add_f32_dpp v199, v199, v199 quad_perm:[2,3,0,1] row_mask:0xf bank_mask:0xf bound_ctrl:1
	v_pk_fma_f32 v[6:7], v[6:7], v[124:125], v[180:181] op_sel:[0,0,0] op_sel_hi:[1,0,1]
	v_add_f32_dpp v198, v198, v198 row_half_mirror row_mask:0xf bank_mask:0xf bound_ctrl:1
	v_add_f32_dpp v199, v199, v199 row_half_mirror row_mask:0xf bank_mask:0xf bound_ctrl:1
	v_pk_fma_f32 v[8:9], v[8:9], v[124:125], v[188:189] op_sel:[0,1,0] op_sel_hi:[1,1,1]
	v_add_f32_dpp v198, v198, v198 row_mirror row_mask:0xf bank_mask:0xf bound_ctrl:1
	v_add_f32_dpp v199, v199, v199 row_mirror row_mask:0xf bank_mask:0xf bound_ctrl:1
	v_pk_fma_f32 v[2:3], v[126:127], v[198:199], v[2:3] op_sel:[0,0,0] op_sel_hi:[0,1,1] neg_lo:[0,1,0] neg_hi:[0,1,0]
	v_pk_fma_f32 v[4:5], v[126:127], v[198:199], v[4:5] op_sel:[1,0,0] op_sel_hi:[1,1,1] neg_lo:[0,1,0] neg_hi:[0,1,0]
	v_pk_mul_f32 v[30:31], v[2:3], v[138:139] op_sel:[0,0] op_sel_hi:[1,0]
	v_pk_fma_f32 v[6:7], v[128:129], v[198:199], v[6:7] op_sel:[0,0,0] op_sel_hi:[0,1,1] neg_lo:[0,1,0] neg_hi:[0,1,0]
	v_pk_fma_f32 v[30:31], v[4:5], v[138:139], v[30:31] op_sel:[0,1,0] op_sel_hi:[1,1,1]
	v_pk_fma_f32 v[8:9], v[128:129], v[198:199], v[8:9] op_sel:[1,0,0] op_sel_hi:[1,1,1] neg_lo:[0,1,0] neg_hi:[0,1,0]
	v_pk_fma_f32 v[30:31], v[6:7], v[140:141], v[30:31] op_sel:[0,0,0] op_sel_hi:[1,0,1]
	v_pk_fma_f32 v[30:31], v[8:9], v[140:141], v[30:31] op_sel:[0,1,0] op_sel_hi:[1,1,1]
	s_waitcnt lgkmcnt(0)
	ds_read_b128 v[134:137], v42 offset:19200
	ds_read_b128 v[130:133], v42 offset:18944
	ds_read_b64 v[142:143], v43 offset:18432
	ds_read_b128 v[122:125], v42 offset:18432
	ds_read_b128 v[126:129], v42 offset:18688
	ds_read_b128 v[138:141], v42 offset:19456
	v_pk_mul_f32 v[198:199], v[2:3], v[166:167] op_sel:[0,0] op_sel_hi:[1,0]
	v_pk_mul_f32 v[176:177], v[174:175], v[162:163] op_sel:[0,0] op_sel_hi:[1,0]
	v_pk_fma_f32 v[198:199], v[4:5], v[166:167], v[198:199] op_sel:[0,1,0] op_sel_hi:[1,1,1]
	v_pk_mul_f32 v[178:179], v[174:175], v[162:163] op_sel:[0,1] op_sel_hi:[1,1]
	v_pk_fma_f32 v[198:199], v[6:7], v[168:169], v[198:199] op_sel:[0,0,0] op_sel_hi:[1,0,1]
	v_pk_mul_f32 v[180:181], v[174:175], v[164:165] op_sel:[0,0] op_sel_hi:[1,0]
	v_pk_fma_f32 v[198:199], v[8:9], v[168:169], v[198:199] op_sel:[0,1,0] op_sel_hi:[1,1,1]
	v_pk_mul_f32 v[188:189], v[174:175], v[164:165] op_sel:[0,1] op_sel_hi:[1,1]
	v_pk_fma_f32 v[2:3], v[2:3], v[154:155], v[176:177] op_sel:[0,0,0] op_sel_hi:[1,0,1]
	v_add_f32_dpp v198, v198, v198 quad_perm:[1,0,3,2] row_mask:0xf bank_mask:0xf bound_ctrl:1
	v_add_f32_dpp v199, v199, v199 quad_perm:[1,0,3,2] row_mask:0xf bank_mask:0xf bound_ctrl:1
	v_pk_fma_f32 v[4:5], v[4:5], v[154:155], v[178:179] op_sel:[0,1,0] op_sel_hi:[1,1,1]
	v_add_f32_dpp v198, v198, v198 quad_perm:[2,3,0,1] row_mask:0xf bank_mask:0xf bound_ctrl:1
	v_add_f32_dpp v199, v199, v199 quad_perm:[2,3,0,1] row_mask:0xf bank_mask:0xf bound_ctrl:1
	v_pk_fma_f32 v[6:7], v[6:7], v[156:157], v[180:181] op_sel:[0,0,0] op_sel_hi:[1,0,1]
	v_add_f32_dpp v198, v198, v198 row_half_mirror row_mask:0xf bank_mask:0xf bound_ctrl:1
	v_add_f32_dpp v199, v199, v199 row_half_mirror row_mask:0xf bank_mask:0xf bound_ctrl:1
	v_pk_fma_f32 v[8:9], v[8:9], v[156:157], v[188:189] op_sel:[0,1,0] op_sel_hi:[1,1,1]
	v_add_f32_dpp v198, v198, v198 row_mirror row_mask:0xf bank_mask:0xf bound_ctrl:1
	v_add_f32_dpp v199, v199, v199 row_mirror row_mask:0xf bank_mask:0xf bound_ctrl:1
	v_pk_fma_f32 v[2:3], v[158:159], v[198:199], v[2:3] op_sel:[0,0,0] op_sel_hi:[0,1,1] neg_lo:[0,1,0] neg_hi:[0,1,0]
	v_pk_fma_f32 v[4:5], v[158:159], v[198:199], v[4:5] op_sel:[1,0,0] op_sel_hi:[1,1,1] neg_lo:[0,1,0] neg_hi:[0,1,0]
	v_pk_mul_f32 v[32:33], v[2:3], v[170:171] op_sel:[0,0] op_sel_hi:[1,0]
	v_pk_fma_f32 v[6:7], v[160:161], v[198:199], v[6:7] op_sel:[0,0,0] op_sel_hi:[0,1,1] neg_lo:[0,1,0] neg_hi:[0,1,0]
	v_pk_fma_f32 v[32:33], v[4:5], v[170:171], v[32:33] op_sel:[0,1,0] op_sel_hi:[1,1,1]
	v_pk_fma_f32 v[8:9], v[160:161], v[198:199], v[8:9] op_sel:[1,0,0] op_sel_hi:[1,1,1] neg_lo:[0,1,0] neg_hi:[0,1,0]
	v_pk_fma_f32 v[32:33], v[6:7], v[172:173], v[32:33] op_sel:[0,0,0] op_sel_hi:[1,0,1]
	v_pk_fma_f32 v[32:33], v[8:9], v[172:173], v[32:33] op_sel:[0,1,0] op_sel_hi:[1,1,1]
	s_waitcnt lgkmcnt(0)
	ds_read_b128 v[166:169], v42 offset:20736
	ds_read_b128 v[162:165], v42 offset:20480
	ds_read_b64 v[174:175], v43 offset:19968
	ds_read_b128 v[154:157], v42 offset:19968
	ds_read_b128 v[158:161], v42 offset:20224
	ds_read_b128 v[170:173], v42 offset:20992
	v_pk_mul_f32 v[198:199], v[2:3], v[134:135] op_sel:[0,0] op_sel_hi:[1,0]
	v_pk_mul_f32 v[176:177], v[142:143], v[130:131] op_sel:[0,0] op_sel_hi:[1,0]
	v_pk_fma_f32 v[198:199], v[4:5], v[134:135], v[198:199] op_sel:[0,1,0] op_sel_hi:[1,1,1]
	v_pk_mul_f32 v[178:179], v[142:143], v[130:131] op_sel:[0,1] op_sel_hi:[1,1]
	v_pk_fma_f32 v[198:199], v[6:7], v[136:137], v[198:199] op_sel:[0,0,0] op_sel_hi:[1,0,1]
	v_pk_mul_f32 v[180:181], v[142:143], v[132:133] op_sel:[0,0] op_sel_hi:[1,0]
	v_pk_fma_f32 v[198:199], v[8:9], v[136:137], v[198:199] op_sel:[0,1,0] op_sel_hi:[1,1,1]
	v_pk_mul_f32 v[188:189], v[142:143], v[132:133] op_sel:[0,1] op_sel_hi:[1,1]
	v_pk_fma_f32 v[2:3], v[2:3], v[122:123], v[176:177] op_sel:[0,0,0] op_sel_hi:[1,0,1]
	v_add_f32_dpp v198, v198, v198 quad_perm:[1,0,3,2] row_mask:0xf bank_mask:0xf bound_ctrl:1
	v_add_f32_dpp v199, v199, v199 quad_perm:[1,0,3,2] row_mask:0xf bank_mask:0xf bound_ctrl:1
	v_pk_fma_f32 v[4:5], v[4:5], v[122:123], v[178:179] op_sel:[0,1,0] op_sel_hi:[1,1,1]
	v_add_f32_dpp v198, v198, v198 quad_perm:[2,3,0,1] row_mask:0xf bank_mask:0xf bound_ctrl:1
	v_add_f32_dpp v199, v199, v199 quad_perm:[2,3,0,1] row_mask:0xf bank_mask:0xf bound_ctrl:1
	v_pk_fma_f32 v[6:7], v[6:7], v[124:125], v[180:181] op_sel:[0,0,0] op_sel_hi:[1,0,1]
	v_add_f32_dpp v198, v198, v198 row_half_mirror row_mask:0xf bank_mask:0xf bound_ctrl:1
	v_add_f32_dpp v199, v199, v199 row_half_mirror row_mask:0xf bank_mask:0xf bound_ctrl:1
	v_pk_fma_f32 v[8:9], v[8:9], v[124:125], v[188:189] op_sel:[0,1,0] op_sel_hi:[1,1,1]
	v_add_f32_dpp v198, v198, v198 row_mirror row_mask:0xf bank_mask:0xf bound_ctrl:1
	v_add_f32_dpp v199, v199, v199 row_mirror row_mask:0xf bank_mask:0xf bound_ctrl:1
	v_pk_fma_f32 v[2:3], v[126:127], v[198:199], v[2:3] op_sel:[0,0,0] op_sel_hi:[0,1,1] neg_lo:[0,1,0] neg_hi:[0,1,0]
	v_pk_fma_f32 v[4:5], v[126:127], v[198:199], v[4:5] op_sel:[1,0,0] op_sel_hi:[1,1,1] neg_lo:[0,1,0] neg_hi:[0,1,0]
	v_pk_mul_f32 v[34:35], v[2:3], v[138:139] op_sel:[0,0] op_sel_hi:[1,0]
	v_pk_fma_f32 v[6:7], v[128:129], v[198:199], v[6:7] op_sel:[0,0,0] op_sel_hi:[0,1,1] neg_lo:[0,1,0] neg_hi:[0,1,0]
	v_pk_fma_f32 v[34:35], v[4:5], v[138:139], v[34:35] op_sel:[0,1,0] op_sel_hi:[1,1,1]
	v_pk_fma_f32 v[8:9], v[128:129], v[198:199], v[8:9] op_sel:[1,0,0] op_sel_hi:[1,1,1] neg_lo:[0,1,0] neg_hi:[0,1,0]
	v_pk_fma_f32 v[34:35], v[6:7], v[140:141], v[34:35] op_sel:[0,0,0] op_sel_hi:[1,0,1]
	v_pk_fma_f32 v[34:35], v[8:9], v[140:141], v[34:35] op_sel:[0,1,0] op_sel_hi:[1,1,1]
	s_waitcnt lgkmcnt(0)
	ds_read_b128 v[134:137], v42 offset:22272
	ds_read_b128 v[130:133], v42 offset:22016
	ds_read_b64 v[142:143], v43 offset:21504
	ds_read_b128 v[122:125], v42 offset:21504
	ds_read_b128 v[126:129], v42 offset:21760
	ds_read_b128 v[138:141], v42 offset:22528
	v_pk_mul_f32 v[198:199], v[2:3], v[166:167] op_sel:[0,0] op_sel_hi:[1,0]
	v_pk_mul_f32 v[176:177], v[174:175], v[162:163] op_sel:[0,0] op_sel_hi:[1,0]
	v_pk_fma_f32 v[198:199], v[4:5], v[166:167], v[198:199] op_sel:[0,1,0] op_sel_hi:[1,1,1]
	v_pk_mul_f32 v[178:179], v[174:175], v[162:163] op_sel:[0,1] op_sel_hi:[1,1]
	v_pk_fma_f32 v[198:199], v[6:7], v[168:169], v[198:199] op_sel:[0,0,0] op_sel_hi:[1,0,1]
	v_pk_mul_f32 v[180:181], v[174:175], v[164:165] op_sel:[0,0] op_sel_hi:[1,0]
	v_pk_fma_f32 v[198:199], v[8:9], v[168:169], v[198:199] op_sel:[0,1,0] op_sel_hi:[1,1,1]
	v_pk_mul_f32 v[188:189], v[174:175], v[164:165] op_sel:[0,1] op_sel_hi:[1,1]
	v_pk_fma_f32 v[2:3], v[2:3], v[154:155], v[176:177] op_sel:[0,0,0] op_sel_hi:[1,0,1]
	v_add_f32_dpp v198, v198, v198 quad_perm:[1,0,3,2] row_mask:0xf bank_mask:0xf bound_ctrl:1
	v_add_f32_dpp v199, v199, v199 quad_perm:[1,0,3,2] row_mask:0xf bank_mask:0xf bound_ctrl:1
	v_pk_fma_f32 v[4:5], v[4:5], v[154:155], v[178:179] op_sel:[0,1,0] op_sel_hi:[1,1,1]
	v_add_f32_dpp v198, v198, v198 quad_perm:[2,3,0,1] row_mask:0xf bank_mask:0xf bound_ctrl:1
	v_add_f32_dpp v199, v199, v199 quad_perm:[2,3,0,1] row_mask:0xf bank_mask:0xf bound_ctrl:1
	v_pk_fma_f32 v[6:7], v[6:7], v[156:157], v[180:181] op_sel:[0,0,0] op_sel_hi:[1,0,1]
	v_add_f32_dpp v198, v198, v198 row_half_mirror row_mask:0xf bank_mask:0xf bound_ctrl:1
	v_add_f32_dpp v199, v199, v199 row_half_mirror row_mask:0xf bank_mask:0xf bound_ctrl:1
	v_pk_fma_f32 v[8:9], v[8:9], v[156:157], v[188:189] op_sel:[0,1,0] op_sel_hi:[1,1,1]
	v_add_f32_dpp v198, v198, v198 row_mirror row_mask:0xf bank_mask:0xf bound_ctrl:1
	v_add_f32_dpp v199, v199, v199 row_mirror row_mask:0xf bank_mask:0xf bound_ctrl:1
	v_pk_fma_f32 v[2:3], v[158:159], v[198:199], v[2:3] op_sel:[0,0,0] op_sel_hi:[0,1,1] neg_lo:[0,1,0] neg_hi:[0,1,0]
	v_pk_fma_f32 v[4:5], v[158:159], v[198:199], v[4:5] op_sel:[1,0,0] op_sel_hi:[1,1,1] neg_lo:[0,1,0] neg_hi:[0,1,0]
	v_pk_mul_f32 v[36:37], v[2:3], v[170:171] op_sel:[0,0] op_sel_hi:[1,0]
	v_pk_fma_f32 v[6:7], v[160:161], v[198:199], v[6:7] op_sel:[0,0,0] op_sel_hi:[0,1,1] neg_lo:[0,1,0] neg_hi:[0,1,0]
	v_pk_fma_f32 v[36:37], v[4:5], v[170:171], v[36:37] op_sel:[0,1,0] op_sel_hi:[1,1,1]
	v_pk_fma_f32 v[8:9], v[160:161], v[198:199], v[8:9] op_sel:[1,0,0] op_sel_hi:[1,1,1] neg_lo:[0,1,0] neg_hi:[0,1,0]
	v_pk_fma_f32 v[36:37], v[6:7], v[172:173], v[36:37] op_sel:[0,0,0] op_sel_hi:[1,0,1]
	v_pk_fma_f32 v[36:37], v[8:9], v[172:173], v[36:37] op_sel:[0,1,0] op_sel_hi:[1,1,1]
	s_waitcnt lgkmcnt(0)
	ds_read_b128 v[166:169], v42 offset:23808
	ds_read_b128 v[162:165], v42 offset:23552
	ds_read_b64 v[174:175], v43 offset:23040
	ds_read_b128 v[154:157], v42 offset:23040
	ds_read_b128 v[158:161], v42 offset:23296
	ds_read_b128 v[170:173], v42 offset:24064
	v_pk_mul_f32 v[198:199], v[2:3], v[134:135] op_sel:[0,0] op_sel_hi:[1,0]
	v_pk_mul_f32 v[176:177], v[142:143], v[130:131] op_sel:[0,0] op_sel_hi:[1,0]
	v_pk_fma_f32 v[198:199], v[4:5], v[134:135], v[198:199] op_sel:[0,1,0] op_sel_hi:[1,1,1]
	v_pk_mul_f32 v[178:179], v[142:143], v[130:131] op_sel:[0,1] op_sel_hi:[1,1]
	v_pk_fma_f32 v[198:199], v[6:7], v[136:137], v[198:199] op_sel:[0,0,0] op_sel_hi:[1,0,1]
	v_pk_mul_f32 v[180:181], v[142:143], v[132:133] op_sel:[0,0] op_sel_hi:[1,0]
	v_pk_fma_f32 v[198:199], v[8:9], v[136:137], v[198:199] op_sel:[0,1,0] op_sel_hi:[1,1,1]
	v_pk_mul_f32 v[188:189], v[142:143], v[132:133] op_sel:[0,1] op_sel_hi:[1,1]
	v_pk_fma_f32 v[2:3], v[2:3], v[122:123], v[176:177] op_sel:[0,0,0] op_sel_hi:[1,0,1]
	v_add_f32_dpp v198, v198, v198 quad_perm:[1,0,3,2] row_mask:0xf bank_mask:0xf bound_ctrl:1
	v_add_f32_dpp v199, v199, v199 quad_perm:[1,0,3,2] row_mask:0xf bank_mask:0xf bound_ctrl:1
	v_pk_fma_f32 v[4:5], v[4:5], v[122:123], v[178:179] op_sel:[0,1,0] op_sel_hi:[1,1,1]
	v_add_f32_dpp v198, v198, v198 quad_perm:[2,3,0,1] row_mask:0xf bank_mask:0xf bound_ctrl:1
	v_add_f32_dpp v199, v199, v199 quad_perm:[2,3,0,1] row_mask:0xf bank_mask:0xf bound_ctrl:1
	v_pk_fma_f32 v[6:7], v[6:7], v[124:125], v[180:181] op_sel:[0,0,0] op_sel_hi:[1,0,1]
	v_add_f32_dpp v198, v198, v198 row_half_mirror row_mask:0xf bank_mask:0xf bound_ctrl:1
	v_add_f32_dpp v199, v199, v199 row_half_mirror row_mask:0xf bank_mask:0xf bound_ctrl:1
	v_pk_fma_f32 v[8:9], v[8:9], v[124:125], v[188:189] op_sel:[0,1,0] op_sel_hi:[1,1,1]
	v_add_f32_dpp v198, v198, v198 row_mirror row_mask:0xf bank_mask:0xf bound_ctrl:1
	v_add_f32_dpp v199, v199, v199 row_mirror row_mask:0xf bank_mask:0xf bound_ctrl:1
	v_pk_fma_f32 v[2:3], v[126:127], v[198:199], v[2:3] op_sel:[0,0,0] op_sel_hi:[0,1,1] neg_lo:[0,1,0] neg_hi:[0,1,0]
	v_pk_fma_f32 v[4:5], v[126:127], v[198:199], v[4:5] op_sel:[1,0,0] op_sel_hi:[1,1,1] neg_lo:[0,1,0] neg_hi:[0,1,0]
	v_pk_mul_f32 v[38:39], v[2:3], v[138:139] op_sel:[0,0] op_sel_hi:[1,0]
	v_pk_fma_f32 v[6:7], v[128:129], v[198:199], v[6:7] op_sel:[0,0,0] op_sel_hi:[0,1,1] neg_lo:[0,1,0] neg_hi:[0,1,0]
	v_pk_fma_f32 v[38:39], v[4:5], v[138:139], v[38:39] op_sel:[0,1,0] op_sel_hi:[1,1,1]
	v_pk_fma_f32 v[8:9], v[128:129], v[198:199], v[8:9] op_sel:[1,0,0] op_sel_hi:[1,1,1] neg_lo:[0,1,0] neg_hi:[0,1,0]
	v_pk_fma_f32 v[38:39], v[6:7], v[140:141], v[38:39] op_sel:[0,0,0] op_sel_hi:[1,0,1]
	v_pk_fma_f32 v[38:39], v[8:9], v[140:141], v[38:39] op_sel:[0,1,0] op_sel_hi:[1,1,1]
	s_waitcnt lgkmcnt(0)
	ds_read_b128 v[134:137], v42 offset:25344
	ds_read_b128 v[130:133], v42 offset:25088
	ds_read_b64 v[142:143], v43 offset:24576
	ds_read_b128 v[122:125], v42 offset:24576
	ds_read_b128 v[126:129], v42 offset:24832
	ds_read_b128 v[138:141], v42 offset:25600
	v_pk_mul_f32 v[198:199], v[2:3], v[166:167] op_sel:[0,0] op_sel_hi:[1,0]
	v_pk_mul_f32 v[176:177], v[174:175], v[162:163] op_sel:[0,0] op_sel_hi:[1,0]
	v_pk_fma_f32 v[198:199], v[4:5], v[166:167], v[198:199] op_sel:[0,1,0] op_sel_hi:[1,1,1]
	v_pk_mul_f32 v[178:179], v[174:175], v[162:163] op_sel:[0,1] op_sel_hi:[1,1]
	v_pk_fma_f32 v[198:199], v[6:7], v[168:169], v[198:199] op_sel:[0,0,0] op_sel_hi:[1,0,1]
	v_pk_mul_f32 v[180:181], v[174:175], v[164:165] op_sel:[0,0] op_sel_hi:[1,0]
	v_pk_fma_f32 v[198:199], v[8:9], v[168:169], v[198:199] op_sel:[0,1,0] op_sel_hi:[1,1,1]
	v_pk_mul_f32 v[188:189], v[174:175], v[164:165] op_sel:[0,1] op_sel_hi:[1,1]
	v_pk_fma_f32 v[2:3], v[2:3], v[154:155], v[176:177] op_sel:[0,0,0] op_sel_hi:[1,0,1]
	v_add_f32_dpp v198, v198, v198 quad_perm:[1,0,3,2] row_mask:0xf bank_mask:0xf bound_ctrl:1
	v_add_f32_dpp v199, v199, v199 quad_perm:[1,0,3,2] row_mask:0xf bank_mask:0xf bound_ctrl:1
	v_pk_fma_f32 v[4:5], v[4:5], v[154:155], v[178:179] op_sel:[0,1,0] op_sel_hi:[1,1,1]
	v_add_f32_dpp v198, v198, v198 quad_perm:[2,3,0,1] row_mask:0xf bank_mask:0xf bound_ctrl:1
	v_add_f32_dpp v199, v199, v199 quad_perm:[2,3,0,1] row_mask:0xf bank_mask:0xf bound_ctrl:1
	v_pk_fma_f32 v[6:7], v[6:7], v[156:157], v[180:181] op_sel:[0,0,0] op_sel_hi:[1,0,1]
	v_add_f32_dpp v198, v198, v198 row_half_mirror row_mask:0xf bank_mask:0xf bound_ctrl:1
	v_add_f32_dpp v199, v199, v199 row_half_mirror row_mask:0xf bank_mask:0xf bound_ctrl:1
	v_pk_fma_f32 v[8:9], v[8:9], v[156:157], v[188:189] op_sel:[0,1,0] op_sel_hi:[1,1,1]
	v_add_f32_dpp v198, v198, v198 row_mirror row_mask:0xf bank_mask:0xf bound_ctrl:1
	v_add_f32_dpp v199, v199, v199 row_mirror row_mask:0xf bank_mask:0xf bound_ctrl:1
	v_pk_fma_f32 v[2:3], v[158:159], v[198:199], v[2:3] op_sel:[0,0,0] op_sel_hi:[0,1,1] neg_lo:[0,1,0] neg_hi:[0,1,0]
	v_pk_fma_f32 v[4:5], v[158:159], v[198:199], v[4:5] op_sel:[1,0,0] op_sel_hi:[1,1,1] neg_lo:[0,1,0] neg_hi:[0,1,0]
	v_pk_mul_f32 v[40:41], v[2:3], v[170:171] op_sel:[0,0] op_sel_hi:[1,0]
	v_pk_fma_f32 v[6:7], v[160:161], v[198:199], v[6:7] op_sel:[0,0,0] op_sel_hi:[0,1,1] neg_lo:[0,1,0] neg_hi:[0,1,0]
	v_pk_fma_f32 v[40:41], v[4:5], v[170:171], v[40:41] op_sel:[0,1,0] op_sel_hi:[1,1,1]
	v_pk_fma_f32 v[8:9], v[160:161], v[198:199], v[8:9] op_sel:[1,0,0] op_sel_hi:[1,1,1] neg_lo:[0,1,0] neg_hi:[0,1,0]
	v_pk_fma_f32 v[40:41], v[6:7], v[172:173], v[40:41] op_sel:[0,0,0] op_sel_hi:[1,0,1]
	v_pk_fma_f32 v[40:41], v[8:9], v[172:173], v[40:41] op_sel:[0,1,0] op_sel_hi:[1,1,1]
	v_add_f32_dpp v190, v10, v10 row_mirror row_mask:0xf bank_mask:0x3
	v_add_f32_dpp v190, v26, v26 row_mirror row_mask:0xf bank_mask:0xc
	v_add_f32_dpp v191, v12, v12 row_mirror row_mask:0xf bank_mask:0x3
	v_add_f32_dpp v191, v28, v28 row_mirror row_mask:0xf bank_mask:0xc
	v_add_f32_dpp v192, v14, v14 row_mirror row_mask:0xf bank_mask:0x3
	v_add_f32_dpp v192, v30, v30 row_mirror row_mask:0xf bank_mask:0xc
	v_add_f32_dpp v193, v16, v16 row_mirror row_mask:0xf bank_mask:0x3
	v_add_f32_dpp v193, v32, v32 row_mirror row_mask:0xf bank_mask:0xc
	v_add_f32_dpp v194, v18, v18 row_mirror row_mask:0xf bank_mask:0x3
	v_add_f32_dpp v194, v34, v34 row_mirror row_mask:0xf bank_mask:0xc
	v_add_f32_dpp v195, v20, v20 row_mirror row_mask:0xf bank_mask:0x3
	v_add_f32_dpp v195, v36, v36 row_mirror row_mask:0xf bank_mask:0xc
	v_add_f32_dpp v196, v22, v22 row_mirror row_mask:0xf bank_mask:0x3
	v_add_f32_dpp v196, v38, v38 row_mirror row_mask:0xf bank_mask:0xc
	v_add_f32_dpp v197, v24, v24 row_mirror row_mask:0xf bank_mask:0x3
	v_add_f32_dpp v197, v40, v40 row_mirror row_mask:0xf bank_mask:0xc
	v_add_f32_dpp v202, v190, v190 row_half_mirror row_mask:0xf bank_mask:0x5
	v_add_f32_dpp v202, v194, v194 row_half_mirror row_mask:0xf bank_mask:0xa
	v_add_f32_dpp v203, v191, v191 row_half_mirror row_mask:0xf bank_mask:0x5
	v_add_f32_dpp v203, v195, v195 row_half_mirror row_mask:0xf bank_mask:0xa
	v_add_f32_dpp v204, v192, v192 row_half_mirror row_mask:0xf bank_mask:0x5
	v_add_f32_dpp v204, v196, v196 row_half_mirror row_mask:0xf bank_mask:0xa
	v_add_f32_dpp v205, v193, v193 row_half_mirror row_mask:0xf bank_mask:0x5
	v_add_f32_dpp v205, v197, v197 row_half_mirror row_mask:0xf bank_mask:0xa
	v_cndmask_b32_e64 v176, v202, v204, s[84:85]
	v_cndmask_b32_e64 v177, v204, v202, s[84:85]
	v_cndmask_b32_e64 v178, v203, v205, s[84:85]
	v_cndmask_b32_e64 v179, v205, v203, s[84:85]
	s_nop 1
	v_add_f32_dpp v210, v177, v176 quad_perm:[2,3,0,1] row_mask:0xf bank_mask:0xf bound_ctrl:1
	v_add_f32_dpp v211, v179, v178 quad_perm:[2,3,0,1] row_mask:0xf bank_mask:0xf bound_ctrl:1
	s_nop 0
	v_cndmask_b32_e64 v176, v210, v211, s[88:89]
	v_cndmask_b32_e64 v177, v211, v210, s[88:89]
	s_nop 1
	v_add_f32_dpp v212, v177, v176 quad_perm:[1,0,3,2] row_mask:0xf bank_mask:0xf bound_ctrl:1
	ds_write_b32 v44, v212 offset:0
	v_add_f32_dpp v190, v11, v11 row_mirror row_mask:0xf bank_mask:0x3
	v_add_f32_dpp v190, v27, v27 row_mirror row_mask:0xf bank_mask:0xc
	v_add_f32_dpp v191, v13, v13 row_mirror row_mask:0xf bank_mask:0x3
	v_add_f32_dpp v191, v29, v29 row_mirror row_mask:0xf bank_mask:0xc
	v_add_f32_dpp v192, v15, v15 row_mirror row_mask:0xf bank_mask:0x3
	v_add_f32_dpp v192, v31, v31 row_mirror row_mask:0xf bank_mask:0xc
	v_add_f32_dpp v193, v17, v17 row_mirror row_mask:0xf bank_mask:0x3
	v_add_f32_dpp v193, v33, v33 row_mirror row_mask:0xf bank_mask:0xc
	v_add_f32_dpp v194, v19, v19 row_mirror row_mask:0xf bank_mask:0x3
	v_add_f32_dpp v194, v35, v35 row_mirror row_mask:0xf bank_mask:0xc
	v_add_f32_dpp v195, v21, v21 row_mirror row_mask:0xf bank_mask:0x3
	v_add_f32_dpp v195, v37, v37 row_mirror row_mask:0xf bank_mask:0xc
	v_add_f32_dpp v196, v23, v23 row_mirror row_mask:0xf bank_mask:0x3
	v_add_f32_dpp v196, v39, v39 row_mirror row_mask:0xf bank_mask:0xc
	v_add_f32_dpp v197, v25, v25 row_mirror row_mask:0xf bank_mask:0x3
	v_add_f32_dpp v197, v41, v41 row_mirror row_mask:0xf bank_mask:0xc
	v_add_f32_dpp v202, v190, v190 row_half_mirror row_mask:0xf bank_mask:0x5
	v_add_f32_dpp v202, v194, v194 row_half_mirror row_mask:0xf bank_mask:0xa
	v_add_f32_dpp v203, v191, v191 row_half_mirror row_mask:0xf bank_mask:0x5
	v_add_f32_dpp v203, v195, v195 row_half_mirror row_mask:0xf bank_mask:0xa
	v_add_f32_dpp v204, v192, v192 row_half_mirror row_mask:0xf bank_mask:0x5
	v_add_f32_dpp v204, v196, v196 row_half_mirror row_mask:0xf bank_mask:0xa
	v_add_f32_dpp v205, v193, v193 row_half_mirror row_mask:0xf bank_mask:0x5
	v_add_f32_dpp v205, v197, v197 row_half_mirror row_mask:0xf bank_mask:0xa
	v_cndmask_b32_e64 v176, v202, v204, s[84:85]
	v_cndmask_b32_e64 v177, v204, v202, s[84:85]
	v_cndmask_b32_e64 v178, v203, v205, s[84:85]
	v_cndmask_b32_e64 v179, v205, v203, s[84:85]
	s_nop 1
	v_add_f32_dpp v210, v177, v176 quad_perm:[2,3,0,1] row_mask:0xf bank_mask:0xf bound_ctrl:1
	v_add_f32_dpp v211, v179, v178 quad_perm:[2,3,0,1] row_mask:0xf bank_mask:0xf bound_ctrl:1
	s_nop 0
	v_cndmask_b32_e64 v176, v210, v211, s[88:89]
	v_cndmask_b32_e64 v177, v211, v210, s[88:89]
	s_nop 1
	v_add_f32_dpp v212, v177, v176 quad_perm:[1,0,3,2] row_mask:0xf bank_mask:0xf bound_ctrl:1
	ds_write_b32 v44, v212 offset:4
	s_waitcnt lgkmcnt(2)
	ds_read_b128 v[166:169], v42 offset:26880
	ds_read_b128 v[162:165], v42 offset:26624
	ds_read_b64 v[174:175], v43 offset:26112
	ds_read_b128 v[154:157], v42 offset:26112
	ds_read_b128 v[158:161], v42 offset:26368
	ds_read_b128 v[170:173], v42 offset:27136
	v_pk_mul_f32 v[198:199], v[2:3], v[134:135] op_sel:[0,0] op_sel_hi:[1,0]
	v_pk_mul_f32 v[176:177], v[142:143], v[130:131] op_sel:[0,0] op_sel_hi:[1,0]
	v_pk_fma_f32 v[198:199], v[4:5], v[134:135], v[198:199] op_sel:[0,1,0] op_sel_hi:[1,1,1]
	v_pk_mul_f32 v[178:179], v[142:143], v[130:131] op_sel:[0,1] op_sel_hi:[1,1]
	v_pk_fma_f32 v[198:199], v[6:7], v[136:137], v[198:199] op_sel:[0,0,0] op_sel_hi:[1,0,1]
	v_pk_mul_f32 v[180:181], v[142:143], v[132:133] op_sel:[0,0] op_sel_hi:[1,0]
	v_pk_fma_f32 v[198:199], v[8:9], v[136:137], v[198:199] op_sel:[0,1,0] op_sel_hi:[1,1,1]
	v_pk_mul_f32 v[188:189], v[142:143], v[132:133] op_sel:[0,1] op_sel_hi:[1,1]
	v_pk_fma_f32 v[2:3], v[2:3], v[122:123], v[176:177] op_sel:[0,0,0] op_sel_hi:[1,0,1]
	v_add_f32_dpp v198, v198, v198 quad_perm:[1,0,3,2] row_mask:0xf bank_mask:0xf bound_ctrl:1
	v_add_f32_dpp v199, v199, v199 quad_perm:[1,0,3,2] row_mask:0xf bank_mask:0xf bound_ctrl:1
	v_pk_fma_f32 v[4:5], v[4:5], v[122:123], v[178:179] op_sel:[0,1,0] op_sel_hi:[1,1,1]
	v_add_f32_dpp v198, v198, v198 quad_perm:[2,3,0,1] row_mask:0xf bank_mask:0xf bound_ctrl:1
	v_add_f32_dpp v199, v199, v199 quad_perm:[2,3,0,1] row_mask:0xf bank_mask:0xf bound_ctrl:1
	v_pk_fma_f32 v[6:7], v[6:7], v[124:125], v[180:181] op_sel:[0,0,0] op_sel_hi:[1,0,1]
	v_add_f32_dpp v198, v198, v198 row_half_mirror row_mask:0xf bank_mask:0xf bound_ctrl:1
	v_add_f32_dpp v199, v199, v199 row_half_mirror row_mask:0xf bank_mask:0xf bound_ctrl:1
	v_pk_fma_f32 v[8:9], v[8:9], v[124:125], v[188:189] op_sel:[0,1,0] op_sel_hi:[1,1,1]
	v_add_f32_dpp v198, v198, v198 row_mirror row_mask:0xf bank_mask:0xf bound_ctrl:1
	v_add_f32_dpp v199, v199, v199 row_mirror row_mask:0xf bank_mask:0xf bound_ctrl:1
	v_pk_fma_f32 v[2:3], v[126:127], v[198:199], v[2:3] op_sel:[0,0,0] op_sel_hi:[0,1,1] neg_lo:[0,1,0] neg_hi:[0,1,0]
	v_pk_fma_f32 v[4:5], v[126:127], v[198:199], v[4:5] op_sel:[1,0,0] op_sel_hi:[1,1,1] neg_lo:[0,1,0] neg_hi:[0,1,0]
	v_pk_mul_f32 v[10:11], v[2:3], v[138:139] op_sel:[0,0] op_sel_hi:[1,0]
	v_pk_fma_f32 v[6:7], v[128:129], v[198:199], v[6:7] op_sel:[0,0,0] op_sel_hi:[0,1,1] neg_lo:[0,1,0] neg_hi:[0,1,0]
	v_pk_fma_f32 v[10:11], v[4:5], v[138:139], v[10:11] op_sel:[0,1,0] op_sel_hi:[1,1,1]
	v_pk_fma_f32 v[8:9], v[128:129], v[198:199], v[8:9] op_sel:[1,0,0] op_sel_hi:[1,1,1] neg_lo:[0,1,0] neg_hi:[0,1,0]
	v_pk_fma_f32 v[10:11], v[6:7], v[140:141], v[10:11] op_sel:[0,0,0] op_sel_hi:[1,0,1]
	v_pk_fma_f32 v[10:11], v[8:9], v[140:141], v[10:11] op_sel:[0,1,0] op_sel_hi:[1,1,1]
	s_waitcnt lgkmcnt(0)
	ds_read_b128 v[134:137], v42 offset:28416
	ds_read_b128 v[130:133], v42 offset:28160
	ds_read_b64 v[142:143], v43 offset:27648
	ds_read_b128 v[122:125], v42 offset:27648
	ds_read_b128 v[126:129], v42 offset:27904
	ds_read_b128 v[138:141], v42 offset:28672
	v_pk_mul_f32 v[198:199], v[2:3], v[166:167] op_sel:[0,0] op_sel_hi:[1,0]
	v_pk_mul_f32 v[176:177], v[174:175], v[162:163] op_sel:[0,0] op_sel_hi:[1,0]
	v_pk_fma_f32 v[198:199], v[4:5], v[166:167], v[198:199] op_sel:[0,1,0] op_sel_hi:[1,1,1]
	v_pk_mul_f32 v[178:179], v[174:175], v[162:163] op_sel:[0,1] op_sel_hi:[1,1]
	v_pk_fma_f32 v[198:199], v[6:7], v[168:169], v[198:199] op_sel:[0,0,0] op_sel_hi:[1,0,1]
	v_pk_mul_f32 v[180:181], v[174:175], v[164:165] op_sel:[0,0] op_sel_hi:[1,0]
	v_pk_fma_f32 v[198:199], v[8:9], v[168:169], v[198:199] op_sel:[0,1,0] op_sel_hi:[1,1,1]
	v_pk_mul_f32 v[188:189], v[174:175], v[164:165] op_sel:[0,1] op_sel_hi:[1,1]
	v_pk_fma_f32 v[2:3], v[2:3], v[154:155], v[176:177] op_sel:[0,0,0] op_sel_hi:[1,0,1]
	v_add_f32_dpp v198, v198, v198 quad_perm:[1,0,3,2] row_mask:0xf bank_mask:0xf bound_ctrl:1
	v_add_f32_dpp v199, v199, v199 quad_perm:[1,0,3,2] row_mask:0xf bank_mask:0xf bound_ctrl:1
	v_pk_fma_f32 v[4:5], v[4:5], v[154:155], v[178:179] op_sel:[0,1,0] op_sel_hi:[1,1,1]
	v_add_f32_dpp v198, v198, v198 quad_perm:[2,3,0,1] row_mask:0xf bank_mask:0xf bound_ctrl:1
	v_add_f32_dpp v199, v199, v199 quad_perm:[2,3,0,1] row_mask:0xf bank_mask:0xf bound_ctrl:1
	v_pk_fma_f32 v[6:7], v[6:7], v[156:157], v[180:181] op_sel:[0,0,0] op_sel_hi:[1,0,1]
	v_add_f32_dpp v198, v198, v198 row_half_mirror row_mask:0xf bank_mask:0xf bound_ctrl:1
	v_add_f32_dpp v199, v199, v199 row_half_mirror row_mask:0xf bank_mask:0xf bound_ctrl:1
	v_pk_fma_f32 v[8:9], v[8:9], v[156:157], v[188:189] op_sel:[0,1,0] op_sel_hi:[1,1,1]
	v_add_f32_dpp v198, v198, v198 row_mirror row_mask:0xf bank_mask:0xf bound_ctrl:1
	v_add_f32_dpp v199, v199, v199 row_mirror row_mask:0xf bank_mask:0xf bound_ctrl:1
	v_pk_fma_f32 v[2:3], v[158:159], v[198:199], v[2:3] op_sel:[0,0,0] op_sel_hi:[0,1,1] neg_lo:[0,1,0] neg_hi:[0,1,0]
	v_pk_fma_f32 v[4:5], v[158:159], v[198:199], v[4:5] op_sel:[1,0,0] op_sel_hi:[1,1,1] neg_lo:[0,1,0] neg_hi:[0,1,0]
	v_pk_mul_f32 v[12:13], v[2:3], v[170:171] op_sel:[0,0] op_sel_hi:[1,0]
	v_pk_fma_f32 v[6:7], v[160:161], v[198:199], v[6:7] op_sel:[0,0,0] op_sel_hi:[0,1,1] neg_lo:[0,1,0] neg_hi:[0,1,0]
	v_pk_fma_f32 v[12:13], v[4:5], v[170:171], v[12:13] op_sel:[0,1,0] op_sel_hi:[1,1,1]
	v_pk_fma_f32 v[8:9], v[160:161], v[198:199], v[8:9] op_sel:[1,0,0] op_sel_hi:[1,1,1] neg_lo:[0,1,0] neg_hi:[0,1,0]
	v_pk_fma_f32 v[12:13], v[6:7], v[172:173], v[12:13] op_sel:[0,0,0] op_sel_hi:[1,0,1]
	v_pk_fma_f32 v[12:13], v[8:9], v[172:173], v[12:13] op_sel:[0,1,0] op_sel_hi:[1,1,1]
	s_waitcnt lgkmcnt(0)
	ds_read_b128 v[166:169], v42 offset:29952
	ds_read_b128 v[162:165], v42 offset:29696
	ds_read_b64 v[174:175], v43 offset:29184
	ds_read_b128 v[154:157], v42 offset:29184
	ds_read_b128 v[158:161], v42 offset:29440
	ds_read_b128 v[170:173], v42 offset:30208
	v_pk_mul_f32 v[198:199], v[2:3], v[134:135] op_sel:[0,0] op_sel_hi:[1,0]
	v_pk_mul_f32 v[176:177], v[142:143], v[130:131] op_sel:[0,0] op_sel_hi:[1,0]
	v_pk_fma_f32 v[198:199], v[4:5], v[134:135], v[198:199] op_sel:[0,1,0] op_sel_hi:[1,1,1]
	v_pk_mul_f32 v[178:179], v[142:143], v[130:131] op_sel:[0,1] op_sel_hi:[1,1]
	v_pk_fma_f32 v[198:199], v[6:7], v[136:137], v[198:199] op_sel:[0,0,0] op_sel_hi:[1,0,1]
	v_pk_mul_f32 v[180:181], v[142:143], v[132:133] op_sel:[0,0] op_sel_hi:[1,0]
	v_pk_fma_f32 v[198:199], v[8:9], v[136:137], v[198:199] op_sel:[0,1,0] op_sel_hi:[1,1,1]
	v_pk_mul_f32 v[188:189], v[142:143], v[132:133] op_sel:[0,1] op_sel_hi:[1,1]
	v_pk_fma_f32 v[2:3], v[2:3], v[122:123], v[176:177] op_sel:[0,0,0] op_sel_hi:[1,0,1]
	v_add_f32_dpp v198, v198, v198 quad_perm:[1,0,3,2] row_mask:0xf bank_mask:0xf bound_ctrl:1
	v_add_f32_dpp v199, v199, v199 quad_perm:[1,0,3,2] row_mask:0xf bank_mask:0xf bound_ctrl:1
	v_pk_fma_f32 v[4:5], v[4:5], v[122:123], v[178:179] op_sel:[0,1,0] op_sel_hi:[1,1,1]
	v_add_f32_dpp v198, v198, v198 quad_perm:[2,3,0,1] row_mask:0xf bank_mask:0xf bound_ctrl:1
	v_add_f32_dpp v199, v199, v199 quad_perm:[2,3,0,1] row_mask:0xf bank_mask:0xf bound_ctrl:1
	v_pk_fma_f32 v[6:7], v[6:7], v[124:125], v[180:181] op_sel:[0,0,0] op_sel_hi:[1,0,1]
	v_add_f32_dpp v198, v198, v198 row_half_mirror row_mask:0xf bank_mask:0xf bound_ctrl:1
	v_add_f32_dpp v199, v199, v199 row_half_mirror row_mask:0xf bank_mask:0xf bound_ctrl:1
	v_pk_fma_f32 v[8:9], v[8:9], v[124:125], v[188:189] op_sel:[0,1,0] op_sel_hi:[1,1,1]
	v_add_f32_dpp v198, v198, v198 row_mirror row_mask:0xf bank_mask:0xf bound_ctrl:1
	v_add_f32_dpp v199, v199, v199 row_mirror row_mask:0xf bank_mask:0xf bound_ctrl:1
	v_pk_fma_f32 v[2:3], v[126:127], v[198:199], v[2:3] op_sel:[0,0,0] op_sel_hi:[0,1,1] neg_lo:[0,1,0] neg_hi:[0,1,0]
	v_pk_fma_f32 v[4:5], v[126:127], v[198:199], v[4:5] op_sel:[1,0,0] op_sel_hi:[1,1,1] neg_lo:[0,1,0] neg_hi:[0,1,0]
	v_pk_mul_f32 v[14:15], v[2:3], v[138:139] op_sel:[0,0] op_sel_hi:[1,0]
	v_pk_fma_f32 v[6:7], v[128:129], v[198:199], v[6:7] op_sel:[0,0,0] op_sel_hi:[0,1,1] neg_lo:[0,1,0] neg_hi:[0,1,0]
	v_pk_fma_f32 v[14:15], v[4:5], v[138:139], v[14:15] op_sel:[0,1,0] op_sel_hi:[1,1,1]
	v_pk_fma_f32 v[8:9], v[128:129], v[198:199], v[8:9] op_sel:[1,0,0] op_sel_hi:[1,1,1] neg_lo:[0,1,0] neg_hi:[0,1,0]
	v_pk_fma_f32 v[14:15], v[6:7], v[140:141], v[14:15] op_sel:[0,0,0] op_sel_hi:[1,0,1]
	v_pk_fma_f32 v[14:15], v[8:9], v[140:141], v[14:15] op_sel:[0,1,0] op_sel_hi:[1,1,1]
	s_waitcnt lgkmcnt(0)
	ds_read_b128 v[134:137], v42 offset:31488
	ds_read_b128 v[130:133], v42 offset:31232
	ds_read_b64 v[142:143], v43 offset:30720
	ds_read_b128 v[122:125], v42 offset:30720
	ds_read_b128 v[126:129], v42 offset:30976
	ds_read_b128 v[138:141], v42 offset:31744
	v_pk_mul_f32 v[198:199], v[2:3], v[166:167] op_sel:[0,0] op_sel_hi:[1,0]
	v_pk_mul_f32 v[176:177], v[174:175], v[162:163] op_sel:[0,0] op_sel_hi:[1,0]
	v_pk_fma_f32 v[198:199], v[4:5], v[166:167], v[198:199] op_sel:[0,1,0] op_sel_hi:[1,1,1]
	v_pk_mul_f32 v[178:179], v[174:175], v[162:163] op_sel:[0,1] op_sel_hi:[1,1]
	v_pk_fma_f32 v[198:199], v[6:7], v[168:169], v[198:199] op_sel:[0,0,0] op_sel_hi:[1,0,1]
	v_pk_mul_f32 v[180:181], v[174:175], v[164:165] op_sel:[0,0] op_sel_hi:[1,0]
	v_pk_fma_f32 v[198:199], v[8:9], v[168:169], v[198:199] op_sel:[0,1,0] op_sel_hi:[1,1,1]
	v_pk_mul_f32 v[188:189], v[174:175], v[164:165] op_sel:[0,1] op_sel_hi:[1,1]
	v_pk_fma_f32 v[2:3], v[2:3], v[154:155], v[176:177] op_sel:[0,0,0] op_sel_hi:[1,0,1]
	v_add_f32_dpp v198, v198, v198 quad_perm:[1,0,3,2] row_mask:0xf bank_mask:0xf bound_ctrl:1
	v_add_f32_dpp v199, v199, v199 quad_perm:[1,0,3,2] row_mask:0xf bank_mask:0xf bound_ctrl:1
	v_pk_fma_f32 v[4:5], v[4:5], v[154:155], v[178:179] op_sel:[0,1,0] op_sel_hi:[1,1,1]
	v_add_f32_dpp v198, v198, v198 quad_perm:[2,3,0,1] row_mask:0xf bank_mask:0xf bound_ctrl:1
	v_add_f32_dpp v199, v199, v199 quad_perm:[2,3,0,1] row_mask:0xf bank_mask:0xf bound_ctrl:1
	v_pk_fma_f32 v[6:7], v[6:7], v[156:157], v[180:181] op_sel:[0,0,0] op_sel_hi:[1,0,1]
	v_add_f32_dpp v198, v198, v198 row_half_mirror row_mask:0xf bank_mask:0xf bound_ctrl:1
	v_add_f32_dpp v199, v199, v199 row_half_mirror row_mask:0xf bank_mask:0xf bound_ctrl:1
	v_pk_fma_f32 v[8:9], v[8:9], v[156:157], v[188:189] op_sel:[0,1,0] op_sel_hi:[1,1,1]
	v_add_f32_dpp v198, v198, v198 row_mirror row_mask:0xf bank_mask:0xf bound_ctrl:1
	v_add_f32_dpp v199, v199, v199 row_mirror row_mask:0xf bank_mask:0xf bound_ctrl:1
	v_pk_fma_f32 v[2:3], v[158:159], v[198:199], v[2:3] op_sel:[0,0,0] op_sel_hi:[0,1,1] neg_lo:[0,1,0] neg_hi:[0,1,0]
	v_pk_fma_f32 v[4:5], v[158:159], v[198:199], v[4:5] op_sel:[1,0,0] op_sel_hi:[1,1,1] neg_lo:[0,1,0] neg_hi:[0,1,0]
	v_pk_mul_f32 v[16:17], v[2:3], v[170:171] op_sel:[0,0] op_sel_hi:[1,0]
	v_pk_fma_f32 v[6:7], v[160:161], v[198:199], v[6:7] op_sel:[0,0,0] op_sel_hi:[0,1,1] neg_lo:[0,1,0] neg_hi:[0,1,0]
	v_pk_fma_f32 v[16:17], v[4:5], v[170:171], v[16:17] op_sel:[0,1,0] op_sel_hi:[1,1,1]
	v_pk_fma_f32 v[8:9], v[160:161], v[198:199], v[8:9] op_sel:[1,0,0] op_sel_hi:[1,1,1] neg_lo:[0,1,0] neg_hi:[0,1,0]
	v_pk_fma_f32 v[16:17], v[6:7], v[172:173], v[16:17] op_sel:[0,0,0] op_sel_hi:[1,0,1]
	v_pk_fma_f32 v[16:17], v[8:9], v[172:173], v[16:17] op_sel:[0,1,0] op_sel_hi:[1,1,1]
	s_waitcnt lgkmcnt(0)
	ds_read_b128 v[166:169], v42 offset:33024
	ds_read_b128 v[162:165], v42 offset:32768
	ds_read_b64 v[174:175], v43 offset:32256
	ds_read_b128 v[154:157], v42 offset:32256
	ds_read_b128 v[158:161], v42 offset:32512
	ds_read_b128 v[170:173], v42 offset:33280
	v_pk_mul_f32 v[198:199], v[2:3], v[134:135] op_sel:[0,0] op_sel_hi:[1,0]
	v_pk_mul_f32 v[176:177], v[142:143], v[130:131] op_sel:[0,0] op_sel_hi:[1,0]
	v_pk_fma_f32 v[198:199], v[4:5], v[134:135], v[198:199] op_sel:[0,1,0] op_sel_hi:[1,1,1]
	v_pk_mul_f32 v[178:179], v[142:143], v[130:131] op_sel:[0,1] op_sel_hi:[1,1]
	v_pk_fma_f32 v[198:199], v[6:7], v[136:137], v[198:199] op_sel:[0,0,0] op_sel_hi:[1,0,1]
	v_pk_mul_f32 v[180:181], v[142:143], v[132:133] op_sel:[0,0] op_sel_hi:[1,0]
	v_pk_fma_f32 v[198:199], v[8:9], v[136:137], v[198:199] op_sel:[0,1,0] op_sel_hi:[1,1,1]
	v_pk_mul_f32 v[188:189], v[142:143], v[132:133] op_sel:[0,1] op_sel_hi:[1,1]
	v_pk_fma_f32 v[2:3], v[2:3], v[122:123], v[176:177] op_sel:[0,0,0] op_sel_hi:[1,0,1]
	v_add_f32_dpp v198, v198, v198 quad_perm:[1,0,3,2] row_mask:0xf bank_mask:0xf bound_ctrl:1
	v_add_f32_dpp v199, v199, v199 quad_perm:[1,0,3,2] row_mask:0xf bank_mask:0xf bound_ctrl:1
	v_pk_fma_f32 v[4:5], v[4:5], v[122:123], v[178:179] op_sel:[0,1,0] op_sel_hi:[1,1,1]
	v_add_f32_dpp v198, v198, v198 quad_perm:[2,3,0,1] row_mask:0xf bank_mask:0xf bound_ctrl:1
	v_add_f32_dpp v199, v199, v199 quad_perm:[2,3,0,1] row_mask:0xf bank_mask:0xf bound_ctrl:1
	v_pk_fma_f32 v[6:7], v[6:7], v[124:125], v[180:181] op_sel:[0,0,0] op_sel_hi:[1,0,1]
	v_add_f32_dpp v198, v198, v198 row_half_mirror row_mask:0xf bank_mask:0xf bound_ctrl:1
	v_add_f32_dpp v199, v199, v199 row_half_mirror row_mask:0xf bank_mask:0xf bound_ctrl:1
	v_pk_fma_f32 v[8:9], v[8:9], v[124:125], v[188:189] op_sel:[0,1,0] op_sel_hi:[1,1,1]
	v_add_f32_dpp v198, v198, v198 row_mirror row_mask:0xf bank_mask:0xf bound_ctrl:1
	v_add_f32_dpp v199, v199, v199 row_mirror row_mask:0xf bank_mask:0xf bound_ctrl:1
	v_pk_fma_f32 v[2:3], v[126:127], v[198:199], v[2:3] op_sel:[0,0,0] op_sel_hi:[0,1,1] neg_lo:[0,1,0] neg_hi:[0,1,0]
	v_pk_fma_f32 v[4:5], v[126:127], v[198:199], v[4:5] op_sel:[1,0,0] op_sel_hi:[1,1,1] neg_lo:[0,1,0] neg_hi:[0,1,0]
	v_pk_mul_f32 v[18:19], v[2:3], v[138:139] op_sel:[0,0] op_sel_hi:[1,0]
	v_pk_fma_f32 v[6:7], v[128:129], v[198:199], v[6:7] op_sel:[0,0,0] op_sel_hi:[0,1,1] neg_lo:[0,1,0] neg_hi:[0,1,0]
	v_pk_fma_f32 v[18:19], v[4:5], v[138:139], v[18:19] op_sel:[0,1,0] op_sel_hi:[1,1,1]
	v_pk_fma_f32 v[8:9], v[128:129], v[198:199], v[8:9] op_sel:[1,0,0] op_sel_hi:[1,1,1] neg_lo:[0,1,0] neg_hi:[0,1,0]
	v_pk_fma_f32 v[18:19], v[6:7], v[140:141], v[18:19] op_sel:[0,0,0] op_sel_hi:[1,0,1]
	v_pk_fma_f32 v[18:19], v[8:9], v[140:141], v[18:19] op_sel:[0,1,0] op_sel_hi:[1,1,1]
	s_waitcnt lgkmcnt(0)
	ds_read_b128 v[134:137], v42 offset:34560
	ds_read_b128 v[130:133], v42 offset:34304
	ds_read_b64 v[142:143], v43 offset:33792
	ds_read_b128 v[122:125], v42 offset:33792
	ds_read_b128 v[126:129], v42 offset:34048
	ds_read_b128 v[138:141], v42 offset:34816
	v_pk_mul_f32 v[198:199], v[2:3], v[166:167] op_sel:[0,0] op_sel_hi:[1,0]
	v_pk_mul_f32 v[176:177], v[174:175], v[162:163] op_sel:[0,0] op_sel_hi:[1,0]
	v_pk_fma_f32 v[198:199], v[4:5], v[166:167], v[198:199] op_sel:[0,1,0] op_sel_hi:[1,1,1]
	v_pk_mul_f32 v[178:179], v[174:175], v[162:163] op_sel:[0,1] op_sel_hi:[1,1]
	v_pk_fma_f32 v[198:199], v[6:7], v[168:169], v[198:199] op_sel:[0,0,0] op_sel_hi:[1,0,1]
	v_pk_mul_f32 v[180:181], v[174:175], v[164:165] op_sel:[0,0] op_sel_hi:[1,0]
	v_pk_fma_f32 v[198:199], v[8:9], v[168:169], v[198:199] op_sel:[0,1,0] op_sel_hi:[1,1,1]
	v_pk_mul_f32 v[188:189], v[174:175], v[164:165] op_sel:[0,1] op_sel_hi:[1,1]
	v_pk_fma_f32 v[2:3], v[2:3], v[154:155], v[176:177] op_sel:[0,0,0] op_sel_hi:[1,0,1]
	v_add_f32_dpp v198, v198, v198 quad_perm:[1,0,3,2] row_mask:0xf bank_mask:0xf bound_ctrl:1
	v_add_f32_dpp v199, v199, v199 quad_perm:[1,0,3,2] row_mask:0xf bank_mask:0xf bound_ctrl:1
	v_pk_fma_f32 v[4:5], v[4:5], v[154:155], v[178:179] op_sel:[0,1,0] op_sel_hi:[1,1,1]
	v_add_f32_dpp v198, v198, v198 quad_perm:[2,3,0,1] row_mask:0xf bank_mask:0xf bound_ctrl:1
	v_add_f32_dpp v199, v199, v199 quad_perm:[2,3,0,1] row_mask:0xf bank_mask:0xf bound_ctrl:1
	v_pk_fma_f32 v[6:7], v[6:7], v[156:157], v[180:181] op_sel:[0,0,0] op_sel_hi:[1,0,1]
	v_add_f32_dpp v198, v198, v198 row_half_mirror row_mask:0xf bank_mask:0xf bound_ctrl:1
	v_add_f32_dpp v199, v199, v199 row_half_mirror row_mask:0xf bank_mask:0xf bound_ctrl:1
	v_pk_fma_f32 v[8:9], v[8:9], v[156:157], v[188:189] op_sel:[0,1,0] op_sel_hi:[1,1,1]
	v_add_f32_dpp v198, v198, v198 row_mirror row_mask:0xf bank_mask:0xf bound_ctrl:1
	v_add_f32_dpp v199, v199, v199 row_mirror row_mask:0xf bank_mask:0xf bound_ctrl:1
	v_pk_fma_f32 v[2:3], v[158:159], v[198:199], v[2:3] op_sel:[0,0,0] op_sel_hi:[0,1,1] neg_lo:[0,1,0] neg_hi:[0,1,0]
	v_pk_fma_f32 v[4:5], v[158:159], v[198:199], v[4:5] op_sel:[1,0,0] op_sel_hi:[1,1,1] neg_lo:[0,1,0] neg_hi:[0,1,0]
	v_pk_mul_f32 v[20:21], v[2:3], v[170:171] op_sel:[0,0] op_sel_hi:[1,0]
	v_pk_fma_f32 v[6:7], v[160:161], v[198:199], v[6:7] op_sel:[0,0,0] op_sel_hi:[0,1,1] neg_lo:[0,1,0] neg_hi:[0,1,0]
	v_pk_fma_f32 v[20:21], v[4:5], v[170:171], v[20:21] op_sel:[0,1,0] op_sel_hi:[1,1,1]
	v_pk_fma_f32 v[8:9], v[160:161], v[198:199], v[8:9] op_sel:[1,0,0] op_sel_hi:[1,1,1] neg_lo:[0,1,0] neg_hi:[0,1,0]
	v_pk_fma_f32 v[20:21], v[6:7], v[172:173], v[20:21] op_sel:[0,0,0] op_sel_hi:[1,0,1]
	v_pk_fma_f32 v[20:21], v[8:9], v[172:173], v[20:21] op_sel:[0,1,0] op_sel_hi:[1,1,1]
	s_waitcnt lgkmcnt(0)
	ds_read_b128 v[166:169], v42 offset:36096
	ds_read_b128 v[162:165], v42 offset:35840
	ds_read_b64 v[174:175], v43 offset:35328
	ds_read_b128 v[154:157], v42 offset:35328
	ds_read_b128 v[158:161], v42 offset:35584
	ds_read_b128 v[170:173], v42 offset:36352
	v_pk_mul_f32 v[198:199], v[2:3], v[134:135] op_sel:[0,0] op_sel_hi:[1,0]
	v_pk_mul_f32 v[176:177], v[142:143], v[130:131] op_sel:[0,0] op_sel_hi:[1,0]
	v_pk_fma_f32 v[198:199], v[4:5], v[134:135], v[198:199] op_sel:[0,1,0] op_sel_hi:[1,1,1]
	v_pk_mul_f32 v[178:179], v[142:143], v[130:131] op_sel:[0,1] op_sel_hi:[1,1]
	v_pk_fma_f32 v[198:199], v[6:7], v[136:137], v[198:199] op_sel:[0,0,0] op_sel_hi:[1,0,1]
	v_pk_mul_f32 v[180:181], v[142:143], v[132:133] op_sel:[0,0] op_sel_hi:[1,0]
	v_pk_fma_f32 v[198:199], v[8:9], v[136:137], v[198:199] op_sel:[0,1,0] op_sel_hi:[1,1,1]
	v_pk_mul_f32 v[188:189], v[142:143], v[132:133] op_sel:[0,1] op_sel_hi:[1,1]
	v_pk_fma_f32 v[2:3], v[2:3], v[122:123], v[176:177] op_sel:[0,0,0] op_sel_hi:[1,0,1]
	v_add_f32_dpp v198, v198, v198 quad_perm:[1,0,3,2] row_mask:0xf bank_mask:0xf bound_ctrl:1
	v_add_f32_dpp v199, v199, v199 quad_perm:[1,0,3,2] row_mask:0xf bank_mask:0xf bound_ctrl:1
	v_pk_fma_f32 v[4:5], v[4:5], v[122:123], v[178:179] op_sel:[0,1,0] op_sel_hi:[1,1,1]
	v_add_f32_dpp v198, v198, v198 quad_perm:[2,3,0,1] row_mask:0xf bank_mask:0xf bound_ctrl:1
	v_add_f32_dpp v199, v199, v199 quad_perm:[2,3,0,1] row_mask:0xf bank_mask:0xf bound_ctrl:1
	v_pk_fma_f32 v[6:7], v[6:7], v[124:125], v[180:181] op_sel:[0,0,0] op_sel_hi:[1,0,1]
	v_add_f32_dpp v198, v198, v198 row_half_mirror row_mask:0xf bank_mask:0xf bound_ctrl:1
	v_add_f32_dpp v199, v199, v199 row_half_mirror row_mask:0xf bank_mask:0xf bound_ctrl:1
	v_pk_fma_f32 v[8:9], v[8:9], v[124:125], v[188:189] op_sel:[0,1,0] op_sel_hi:[1,1,1]
	v_add_f32_dpp v198, v198, v198 row_mirror row_mask:0xf bank_mask:0xf bound_ctrl:1
	v_add_f32_dpp v199, v199, v199 row_mirror row_mask:0xf bank_mask:0xf bound_ctrl:1
	v_pk_fma_f32 v[2:3], v[126:127], v[198:199], v[2:3] op_sel:[0,0,0] op_sel_hi:[0,1,1] neg_lo:[0,1,0] neg_hi:[0,1,0]
	v_pk_fma_f32 v[4:5], v[126:127], v[198:199], v[4:5] op_sel:[1,0,0] op_sel_hi:[1,1,1] neg_lo:[0,1,0] neg_hi:[0,1,0]
	v_pk_mul_f32 v[22:23], v[2:3], v[138:139] op_sel:[0,0] op_sel_hi:[1,0]
	v_pk_fma_f32 v[6:7], v[128:129], v[198:199], v[6:7] op_sel:[0,0,0] op_sel_hi:[0,1,1] neg_lo:[0,1,0] neg_hi:[0,1,0]
	v_pk_fma_f32 v[22:23], v[4:5], v[138:139], v[22:23] op_sel:[0,1,0] op_sel_hi:[1,1,1]
	v_pk_fma_f32 v[8:9], v[128:129], v[198:199], v[8:9] op_sel:[1,0,0] op_sel_hi:[1,1,1] neg_lo:[0,1,0] neg_hi:[0,1,0]
	v_pk_fma_f32 v[22:23], v[6:7], v[140:141], v[22:23] op_sel:[0,0,0] op_sel_hi:[1,0,1]
	v_pk_fma_f32 v[22:23], v[8:9], v[140:141], v[22:23] op_sel:[0,1,0] op_sel_hi:[1,1,1]
	s_waitcnt lgkmcnt(0)
	ds_read_b128 v[134:137], v42 offset:37632
	ds_read_b128 v[130:133], v42 offset:37376
	ds_read_b64 v[142:143], v43 offset:36864
	ds_read_b128 v[122:125], v42 offset:36864
	ds_read_b128 v[126:129], v42 offset:37120
	ds_read_b128 v[138:141], v42 offset:37888
	v_pk_mul_f32 v[198:199], v[2:3], v[166:167] op_sel:[0,0] op_sel_hi:[1,0]
	v_pk_mul_f32 v[176:177], v[174:175], v[162:163] op_sel:[0,0] op_sel_hi:[1,0]
	v_pk_fma_f32 v[198:199], v[4:5], v[166:167], v[198:199] op_sel:[0,1,0] op_sel_hi:[1,1,1]
	v_pk_mul_f32 v[178:179], v[174:175], v[162:163] op_sel:[0,1] op_sel_hi:[1,1]
	v_pk_fma_f32 v[198:199], v[6:7], v[168:169], v[198:199] op_sel:[0,0,0] op_sel_hi:[1,0,1]
	v_pk_mul_f32 v[180:181], v[174:175], v[164:165] op_sel:[0,0] op_sel_hi:[1,0]
	v_pk_fma_f32 v[198:199], v[8:9], v[168:169], v[198:199] op_sel:[0,1,0] op_sel_hi:[1,1,1]
	v_pk_mul_f32 v[188:189], v[174:175], v[164:165] op_sel:[0,1] op_sel_hi:[1,1]
	v_pk_fma_f32 v[2:3], v[2:3], v[154:155], v[176:177] op_sel:[0,0,0] op_sel_hi:[1,0,1]
	v_add_f32_dpp v198, v198, v198 quad_perm:[1,0,3,2] row_mask:0xf bank_mask:0xf bound_ctrl:1
	v_add_f32_dpp v199, v199, v199 quad_perm:[1,0,3,2] row_mask:0xf bank_mask:0xf bound_ctrl:1
	v_pk_fma_f32 v[4:5], v[4:5], v[154:155], v[178:179] op_sel:[0,1,0] op_sel_hi:[1,1,1]
	v_add_f32_dpp v198, v198, v198 quad_perm:[2,3,0,1] row_mask:0xf bank_mask:0xf bound_ctrl:1
	v_add_f32_dpp v199, v199, v199 quad_perm:[2,3,0,1] row_mask:0xf bank_mask:0xf bound_ctrl:1
	v_pk_fma_f32 v[6:7], v[6:7], v[156:157], v[180:181] op_sel:[0,0,0] op_sel_hi:[1,0,1]
	v_add_f32_dpp v198, v198, v198 row_half_mirror row_mask:0xf bank_mask:0xf bound_ctrl:1
	v_add_f32_dpp v199, v199, v199 row_half_mirror row_mask:0xf bank_mask:0xf bound_ctrl:1
	v_pk_fma_f32 v[8:9], v[8:9], v[156:157], v[188:189] op_sel:[0,1,0] op_sel_hi:[1,1,1]
	v_add_f32_dpp v198, v198, v198 row_mirror row_mask:0xf bank_mask:0xf bound_ctrl:1
	v_add_f32_dpp v199, v199, v199 row_mirror row_mask:0xf bank_mask:0xf bound_ctrl:1
	v_pk_fma_f32 v[2:3], v[158:159], v[198:199], v[2:3] op_sel:[0,0,0] op_sel_hi:[0,1,1] neg_lo:[0,1,0] neg_hi:[0,1,0]
	v_pk_fma_f32 v[4:5], v[158:159], v[198:199], v[4:5] op_sel:[1,0,0] op_sel_hi:[1,1,1] neg_lo:[0,1,0] neg_hi:[0,1,0]
	v_pk_mul_f32 v[24:25], v[2:3], v[170:171] op_sel:[0,0] op_sel_hi:[1,0]
	v_pk_fma_f32 v[6:7], v[160:161], v[198:199], v[6:7] op_sel:[0,0,0] op_sel_hi:[0,1,1] neg_lo:[0,1,0] neg_hi:[0,1,0]
	v_pk_fma_f32 v[24:25], v[4:5], v[170:171], v[24:25] op_sel:[0,1,0] op_sel_hi:[1,1,1]
	v_pk_fma_f32 v[8:9], v[160:161], v[198:199], v[8:9] op_sel:[1,0,0] op_sel_hi:[1,1,1] neg_lo:[0,1,0] neg_hi:[0,1,0]
	v_pk_fma_f32 v[24:25], v[6:7], v[172:173], v[24:25] op_sel:[0,0,0] op_sel_hi:[1,0,1]
	v_pk_fma_f32 v[24:25], v[8:9], v[172:173], v[24:25] op_sel:[0,1,0] op_sel_hi:[1,1,1]
	s_waitcnt lgkmcnt(0)
	ds_read_b128 v[166:169], v42 offset:39168
	ds_read_b128 v[162:165], v42 offset:38912
	ds_read_b64 v[174:175], v43 offset:38400
	ds_read_b128 v[154:157], v42 offset:38400
	ds_read_b128 v[158:161], v42 offset:38656
	ds_read_b128 v[170:173], v42 offset:39424
	v_pk_mul_f32 v[198:199], v[2:3], v[134:135] op_sel:[0,0] op_sel_hi:[1,0]
	v_pk_mul_f32 v[176:177], v[142:143], v[130:131] op_sel:[0,0] op_sel_hi:[1,0]
	v_pk_fma_f32 v[198:199], v[4:5], v[134:135], v[198:199] op_sel:[0,1,0] op_sel_hi:[1,1,1]
	v_pk_mul_f32 v[178:179], v[142:143], v[130:131] op_sel:[0,1] op_sel_hi:[1,1]
	v_pk_fma_f32 v[198:199], v[6:7], v[136:137], v[198:199] op_sel:[0,0,0] op_sel_hi:[1,0,1]
	v_pk_mul_f32 v[180:181], v[142:143], v[132:133] op_sel:[0,0] op_sel_hi:[1,0]
	v_pk_fma_f32 v[198:199], v[8:9], v[136:137], v[198:199] op_sel:[0,1,0] op_sel_hi:[1,1,1]
	v_pk_mul_f32 v[188:189], v[142:143], v[132:133] op_sel:[0,1] op_sel_hi:[1,1]
	v_pk_fma_f32 v[2:3], v[2:3], v[122:123], v[176:177] op_sel:[0,0,0] op_sel_hi:[1,0,1]
	v_add_f32_dpp v198, v198, v198 quad_perm:[1,0,3,2] row_mask:0xf bank_mask:0xf bound_ctrl:1
	v_add_f32_dpp v199, v199, v199 quad_perm:[1,0,3,2] row_mask:0xf bank_mask:0xf bound_ctrl:1
	v_pk_fma_f32 v[4:5], v[4:5], v[122:123], v[178:179] op_sel:[0,1,0] op_sel_hi:[1,1,1]
	v_add_f32_dpp v198, v198, v198 quad_perm:[2,3,0,1] row_mask:0xf bank_mask:0xf bound_ctrl:1
	v_add_f32_dpp v199, v199, v199 quad_perm:[2,3,0,1] row_mask:0xf bank_mask:0xf bound_ctrl:1
	v_pk_fma_f32 v[6:7], v[6:7], v[124:125], v[180:181] op_sel:[0,0,0] op_sel_hi:[1,0,1]
	v_add_f32_dpp v198, v198, v198 row_half_mirror row_mask:0xf bank_mask:0xf bound_ctrl:1
	v_add_f32_dpp v199, v199, v199 row_half_mirror row_mask:0xf bank_mask:0xf bound_ctrl:1
	v_pk_fma_f32 v[8:9], v[8:9], v[124:125], v[188:189] op_sel:[0,1,0] op_sel_hi:[1,1,1]
	v_add_f32_dpp v198, v198, v198 row_mirror row_mask:0xf bank_mask:0xf bound_ctrl:1
	v_add_f32_dpp v199, v199, v199 row_mirror row_mask:0xf bank_mask:0xf bound_ctrl:1
	v_pk_fma_f32 v[2:3], v[126:127], v[198:199], v[2:3] op_sel:[0,0,0] op_sel_hi:[0,1,1] neg_lo:[0,1,0] neg_hi:[0,1,0]
	v_pk_fma_f32 v[4:5], v[126:127], v[198:199], v[4:5] op_sel:[1,0,0] op_sel_hi:[1,1,1] neg_lo:[0,1,0] neg_hi:[0,1,0]
	v_pk_mul_f32 v[26:27], v[2:3], v[138:139] op_sel:[0,0] op_sel_hi:[1,0]
	v_pk_fma_f32 v[6:7], v[128:129], v[198:199], v[6:7] op_sel:[0,0,0] op_sel_hi:[0,1,1] neg_lo:[0,1,0] neg_hi:[0,1,0]
	v_pk_fma_f32 v[26:27], v[4:5], v[138:139], v[26:27] op_sel:[0,1,0] op_sel_hi:[1,1,1]
	v_pk_fma_f32 v[8:9], v[128:129], v[198:199], v[8:9] op_sel:[1,0,0] op_sel_hi:[1,1,1] neg_lo:[0,1,0] neg_hi:[0,1,0]
	v_pk_fma_f32 v[26:27], v[6:7], v[140:141], v[26:27] op_sel:[0,0,0] op_sel_hi:[1,0,1]
	v_pk_fma_f32 v[26:27], v[8:9], v[140:141], v[26:27] op_sel:[0,1,0] op_sel_hi:[1,1,1]
	s_waitcnt lgkmcnt(0)
	ds_read_b128 v[134:137], v42 offset:40704
	ds_read_b128 v[130:133], v42 offset:40448
	ds_read_b64 v[142:143], v43 offset:39936
	ds_read_b128 v[122:125], v42 offset:39936
	ds_read_b128 v[126:129], v42 offset:40192
	ds_read_b128 v[138:141], v42 offset:40960
	v_pk_mul_f32 v[198:199], v[2:3], v[166:167] op_sel:[0,0] op_sel_hi:[1,0]
	v_pk_mul_f32 v[176:177], v[174:175], v[162:163] op_sel:[0,0] op_sel_hi:[1,0]
	v_pk_fma_f32 v[198:199], v[4:5], v[166:167], v[198:199] op_sel:[0,1,0] op_sel_hi:[1,1,1]
	v_pk_mul_f32 v[178:179], v[174:175], v[162:163] op_sel:[0,1] op_sel_hi:[1,1]
	v_pk_fma_f32 v[198:199], v[6:7], v[168:169], v[198:199] op_sel:[0,0,0] op_sel_hi:[1,0,1]
	v_pk_mul_f32 v[180:181], v[174:175], v[164:165] op_sel:[0,0] op_sel_hi:[1,0]
	v_pk_fma_f32 v[198:199], v[8:9], v[168:169], v[198:199] op_sel:[0,1,0] op_sel_hi:[1,1,1]
	v_pk_mul_f32 v[188:189], v[174:175], v[164:165] op_sel:[0,1] op_sel_hi:[1,1]
	v_pk_fma_f32 v[2:3], v[2:3], v[154:155], v[176:177] op_sel:[0,0,0] op_sel_hi:[1,0,1]
	v_add_f32_dpp v198, v198, v198 quad_perm:[1,0,3,2] row_mask:0xf bank_mask:0xf bound_ctrl:1
	v_add_f32_dpp v199, v199, v199 quad_perm:[1,0,3,2] row_mask:0xf bank_mask:0xf bound_ctrl:1
	v_pk_fma_f32 v[4:5], v[4:5], v[154:155], v[178:179] op_sel:[0,1,0] op_sel_hi:[1,1,1]
	v_add_f32_dpp v198, v198, v198 quad_perm:[2,3,0,1] row_mask:0xf bank_mask:0xf bound_ctrl:1
	v_add_f32_dpp v199, v199, v199 quad_perm:[2,3,0,1] row_mask:0xf bank_mask:0xf bound_ctrl:1
	v_pk_fma_f32 v[6:7], v[6:7], v[156:157], v[180:181] op_sel:[0,0,0] op_sel_hi:[1,0,1]
	v_add_f32_dpp v198, v198, v198 row_half_mirror row_mask:0xf bank_mask:0xf bound_ctrl:1
	v_add_f32_dpp v199, v199, v199 row_half_mirror row_mask:0xf bank_mask:0xf bound_ctrl:1
	v_pk_fma_f32 v[8:9], v[8:9], v[156:157], v[188:189] op_sel:[0,1,0] op_sel_hi:[1,1,1]
	v_add_f32_dpp v198, v198, v198 row_mirror row_mask:0xf bank_mask:0xf bound_ctrl:1
	v_add_f32_dpp v199, v199, v199 row_mirror row_mask:0xf bank_mask:0xf bound_ctrl:1
	v_pk_fma_f32 v[2:3], v[158:159], v[198:199], v[2:3] op_sel:[0,0,0] op_sel_hi:[0,1,1] neg_lo:[0,1,0] neg_hi:[0,1,0]
	v_pk_fma_f32 v[4:5], v[158:159], v[198:199], v[4:5] op_sel:[1,0,0] op_sel_hi:[1,1,1] neg_lo:[0,1,0] neg_hi:[0,1,0]
	v_pk_mul_f32 v[28:29], v[2:3], v[170:171] op_sel:[0,0] op_sel_hi:[1,0]
	v_pk_fma_f32 v[6:7], v[160:161], v[198:199], v[6:7] op_sel:[0,0,0] op_sel_hi:[0,1,1] neg_lo:[0,1,0] neg_hi:[0,1,0]
	v_pk_fma_f32 v[28:29], v[4:5], v[170:171], v[28:29] op_sel:[0,1,0] op_sel_hi:[1,1,1]
	v_pk_fma_f32 v[8:9], v[160:161], v[198:199], v[8:9] op_sel:[1,0,0] op_sel_hi:[1,1,1] neg_lo:[0,1,0] neg_hi:[0,1,0]
	v_pk_fma_f32 v[28:29], v[6:7], v[172:173], v[28:29] op_sel:[0,0,0] op_sel_hi:[1,0,1]
	v_pk_fma_f32 v[28:29], v[8:9], v[172:173], v[28:29] op_sel:[0,1,0] op_sel_hi:[1,1,1]
	s_waitcnt lgkmcnt(0)
	ds_read_b128 v[166:169], v42 offset:42240
	ds_read_b128 v[162:165], v42 offset:41984
	ds_read_b64 v[174:175], v43 offset:41472
	ds_read_b128 v[154:157], v42 offset:41472
	ds_read_b128 v[158:161], v42 offset:41728
	ds_read_b128 v[170:173], v42 offset:42496
	v_pk_mul_f32 v[198:199], v[2:3], v[134:135] op_sel:[0,0] op_sel_hi:[1,0]
	v_pk_mul_f32 v[176:177], v[142:143], v[130:131] op_sel:[0,0] op_sel_hi:[1,0]
	v_pk_fma_f32 v[198:199], v[4:5], v[134:135], v[198:199] op_sel:[0,1,0] op_sel_hi:[1,1,1]
	v_pk_mul_f32 v[178:179], v[142:143], v[130:131] op_sel:[0,1] op_sel_hi:[1,1]
	v_pk_fma_f32 v[198:199], v[6:7], v[136:137], v[198:199] op_sel:[0,0,0] op_sel_hi:[1,0,1]
	v_pk_mul_f32 v[180:181], v[142:143], v[132:133] op_sel:[0,0] op_sel_hi:[1,0]
	v_pk_fma_f32 v[198:199], v[8:9], v[136:137], v[198:199] op_sel:[0,1,0] op_sel_hi:[1,1,1]
	v_pk_mul_f32 v[188:189], v[142:143], v[132:133] op_sel:[0,1] op_sel_hi:[1,1]
	v_pk_fma_f32 v[2:3], v[2:3], v[122:123], v[176:177] op_sel:[0,0,0] op_sel_hi:[1,0,1]
	v_add_f32_dpp v198, v198, v198 quad_perm:[1,0,3,2] row_mask:0xf bank_mask:0xf bound_ctrl:1
	v_add_f32_dpp v199, v199, v199 quad_perm:[1,0,3,2] row_mask:0xf bank_mask:0xf bound_ctrl:1
	v_pk_fma_f32 v[4:5], v[4:5], v[122:123], v[178:179] op_sel:[0,1,0] op_sel_hi:[1,1,1]
	v_add_f32_dpp v198, v198, v198 quad_perm:[2,3,0,1] row_mask:0xf bank_mask:0xf bound_ctrl:1
	v_add_f32_dpp v199, v199, v199 quad_perm:[2,3,0,1] row_mask:0xf bank_mask:0xf bound_ctrl:1
	v_pk_fma_f32 v[6:7], v[6:7], v[124:125], v[180:181] op_sel:[0,0,0] op_sel_hi:[1,0,1]
	v_add_f32_dpp v198, v198, v198 row_half_mirror row_mask:0xf bank_mask:0xf bound_ctrl:1
	v_add_f32_dpp v199, v199, v199 row_half_mirror row_mask:0xf bank_mask:0xf bound_ctrl:1
	v_pk_fma_f32 v[8:9], v[8:9], v[124:125], v[188:189] op_sel:[0,1,0] op_sel_hi:[1,1,1]
	v_add_f32_dpp v198, v198, v198 row_mirror row_mask:0xf bank_mask:0xf bound_ctrl:1
	v_add_f32_dpp v199, v199, v199 row_mirror row_mask:0xf bank_mask:0xf bound_ctrl:1
	v_pk_fma_f32 v[2:3], v[126:127], v[198:199], v[2:3] op_sel:[0,0,0] op_sel_hi:[0,1,1] neg_lo:[0,1,0] neg_hi:[0,1,0]
	v_pk_fma_f32 v[4:5], v[126:127], v[198:199], v[4:5] op_sel:[1,0,0] op_sel_hi:[1,1,1] neg_lo:[0,1,0] neg_hi:[0,1,0]
	v_pk_mul_f32 v[30:31], v[2:3], v[138:139] op_sel:[0,0] op_sel_hi:[1,0]
	v_pk_fma_f32 v[6:7], v[128:129], v[198:199], v[6:7] op_sel:[0,0,0] op_sel_hi:[0,1,1] neg_lo:[0,1,0] neg_hi:[0,1,0]
	v_pk_fma_f32 v[30:31], v[4:5], v[138:139], v[30:31] op_sel:[0,1,0] op_sel_hi:[1,1,1]
	v_pk_fma_f32 v[8:9], v[128:129], v[198:199], v[8:9] op_sel:[1,0,0] op_sel_hi:[1,1,1] neg_lo:[0,1,0] neg_hi:[0,1,0]
	v_pk_fma_f32 v[30:31], v[6:7], v[140:141], v[30:31] op_sel:[0,0,0] op_sel_hi:[1,0,1]
	v_pk_fma_f32 v[30:31], v[8:9], v[140:141], v[30:31] op_sel:[0,1,0] op_sel_hi:[1,1,1]
	s_waitcnt lgkmcnt(0)
	ds_read_b128 v[134:137], v42 offset:43776
	ds_read_b128 v[130:133], v42 offset:43520
	ds_read_b64 v[142:143], v43 offset:43008
	ds_read_b128 v[122:125], v42 offset:43008
	ds_read_b128 v[126:129], v42 offset:43264
	ds_read_b128 v[138:141], v42 offset:44032
	v_pk_mul_f32 v[198:199], v[2:3], v[166:167] op_sel:[0,0] op_sel_hi:[1,0]
	v_pk_mul_f32 v[176:177], v[174:175], v[162:163] op_sel:[0,0] op_sel_hi:[1,0]
	v_pk_fma_f32 v[198:199], v[4:5], v[166:167], v[198:199] op_sel:[0,1,0] op_sel_hi:[1,1,1]
	v_pk_mul_f32 v[178:179], v[174:175], v[162:163] op_sel:[0,1] op_sel_hi:[1,1]
	v_pk_fma_f32 v[198:199], v[6:7], v[168:169], v[198:199] op_sel:[0,0,0] op_sel_hi:[1,0,1]
	v_pk_mul_f32 v[180:181], v[174:175], v[164:165] op_sel:[0,0] op_sel_hi:[1,0]
	v_pk_fma_f32 v[198:199], v[8:9], v[168:169], v[198:199] op_sel:[0,1,0] op_sel_hi:[1,1,1]
	v_pk_mul_f32 v[188:189], v[174:175], v[164:165] op_sel:[0,1] op_sel_hi:[1,1]
	v_pk_fma_f32 v[2:3], v[2:3], v[154:155], v[176:177] op_sel:[0,0,0] op_sel_hi:[1,0,1]
	v_add_f32_dpp v198, v198, v198 quad_perm:[1,0,3,2] row_mask:0xf bank_mask:0xf bound_ctrl:1
	v_add_f32_dpp v199, v199, v199 quad_perm:[1,0,3,2] row_mask:0xf bank_mask:0xf bound_ctrl:1
	v_pk_fma_f32 v[4:5], v[4:5], v[154:155], v[178:179] op_sel:[0,1,0] op_sel_hi:[1,1,1]
	v_add_f32_dpp v198, v198, v198 quad_perm:[2,3,0,1] row_mask:0xf bank_mask:0xf bound_ctrl:1
	v_add_f32_dpp v199, v199, v199 quad_perm:[2,3,0,1] row_mask:0xf bank_mask:0xf bound_ctrl:1
	v_pk_fma_f32 v[6:7], v[6:7], v[156:157], v[180:181] op_sel:[0,0,0] op_sel_hi:[1,0,1]
	v_add_f32_dpp v198, v198, v198 row_half_mirror row_mask:0xf bank_mask:0xf bound_ctrl:1
	v_add_f32_dpp v199, v199, v199 row_half_mirror row_mask:0xf bank_mask:0xf bound_ctrl:1
	v_pk_fma_f32 v[8:9], v[8:9], v[156:157], v[188:189] op_sel:[0,1,0] op_sel_hi:[1,1,1]
	v_add_f32_dpp v198, v198, v198 row_mirror row_mask:0xf bank_mask:0xf bound_ctrl:1
	v_add_f32_dpp v199, v199, v199 row_mirror row_mask:0xf bank_mask:0xf bound_ctrl:1
	v_pk_fma_f32 v[2:3], v[158:159], v[198:199], v[2:3] op_sel:[0,0,0] op_sel_hi:[0,1,1] neg_lo:[0,1,0] neg_hi:[0,1,0]
	v_pk_fma_f32 v[4:5], v[158:159], v[198:199], v[4:5] op_sel:[1,0,0] op_sel_hi:[1,1,1] neg_lo:[0,1,0] neg_hi:[0,1,0]
	v_pk_mul_f32 v[32:33], v[2:3], v[170:171] op_sel:[0,0] op_sel_hi:[1,0]
	v_pk_fma_f32 v[6:7], v[160:161], v[198:199], v[6:7] op_sel:[0,0,0] op_sel_hi:[0,1,1] neg_lo:[0,1,0] neg_hi:[0,1,0]
	v_pk_fma_f32 v[32:33], v[4:5], v[170:171], v[32:33] op_sel:[0,1,0] op_sel_hi:[1,1,1]
	v_pk_fma_f32 v[8:9], v[160:161], v[198:199], v[8:9] op_sel:[1,0,0] op_sel_hi:[1,1,1] neg_lo:[0,1,0] neg_hi:[0,1,0]
	v_pk_fma_f32 v[32:33], v[6:7], v[172:173], v[32:33] op_sel:[0,0,0] op_sel_hi:[1,0,1]
	v_pk_fma_f32 v[32:33], v[8:9], v[172:173], v[32:33] op_sel:[0,1,0] op_sel_hi:[1,1,1]
	s_waitcnt lgkmcnt(0)
	ds_read_b128 v[166:169], v42 offset:45312
	ds_read_b128 v[162:165], v42 offset:45056
	ds_read_b64 v[174:175], v43 offset:44544
	ds_read_b128 v[154:157], v42 offset:44544
	ds_read_b128 v[158:161], v42 offset:44800
	ds_read_b128 v[170:173], v42 offset:45568
	v_pk_mul_f32 v[198:199], v[2:3], v[134:135] op_sel:[0,0] op_sel_hi:[1,0]
	v_pk_mul_f32 v[176:177], v[142:143], v[130:131] op_sel:[0,0] op_sel_hi:[1,0]
	v_pk_fma_f32 v[198:199], v[4:5], v[134:135], v[198:199] op_sel:[0,1,0] op_sel_hi:[1,1,1]
	v_pk_mul_f32 v[178:179], v[142:143], v[130:131] op_sel:[0,1] op_sel_hi:[1,1]
	v_pk_fma_f32 v[198:199], v[6:7], v[136:137], v[198:199] op_sel:[0,0,0] op_sel_hi:[1,0,1]
	v_pk_mul_f32 v[180:181], v[142:143], v[132:133] op_sel:[0,0] op_sel_hi:[1,0]
	v_pk_fma_f32 v[198:199], v[8:9], v[136:137], v[198:199] op_sel:[0,1,0] op_sel_hi:[1,1,1]
	v_pk_mul_f32 v[188:189], v[142:143], v[132:133] op_sel:[0,1] op_sel_hi:[1,1]
	v_pk_fma_f32 v[2:3], v[2:3], v[122:123], v[176:177] op_sel:[0,0,0] op_sel_hi:[1,0,1]
	v_add_f32_dpp v198, v198, v198 quad_perm:[1,0,3,2] row_mask:0xf bank_mask:0xf bound_ctrl:1
	v_add_f32_dpp v199, v199, v199 quad_perm:[1,0,3,2] row_mask:0xf bank_mask:0xf bound_ctrl:1
	v_pk_fma_f32 v[4:5], v[4:5], v[122:123], v[178:179] op_sel:[0,1,0] op_sel_hi:[1,1,1]
	v_add_f32_dpp v198, v198, v198 quad_perm:[2,3,0,1] row_mask:0xf bank_mask:0xf bound_ctrl:1
	v_add_f32_dpp v199, v199, v199 quad_perm:[2,3,0,1] row_mask:0xf bank_mask:0xf bound_ctrl:1
	v_pk_fma_f32 v[6:7], v[6:7], v[124:125], v[180:181] op_sel:[0,0,0] op_sel_hi:[1,0,1]
	v_add_f32_dpp v198, v198, v198 row_half_mirror row_mask:0xf bank_mask:0xf bound_ctrl:1
	v_add_f32_dpp v199, v199, v199 row_half_mirror row_mask:0xf bank_mask:0xf bound_ctrl:1
	v_pk_fma_f32 v[8:9], v[8:9], v[124:125], v[188:189] op_sel:[0,1,0] op_sel_hi:[1,1,1]
	v_add_f32_dpp v198, v198, v198 row_mirror row_mask:0xf bank_mask:0xf bound_ctrl:1
	v_add_f32_dpp v199, v199, v199 row_mirror row_mask:0xf bank_mask:0xf bound_ctrl:1
	v_pk_fma_f32 v[2:3], v[126:127], v[198:199], v[2:3] op_sel:[0,0,0] op_sel_hi:[0,1,1] neg_lo:[0,1,0] neg_hi:[0,1,0]
	v_pk_fma_f32 v[4:5], v[126:127], v[198:199], v[4:5] op_sel:[1,0,0] op_sel_hi:[1,1,1] neg_lo:[0,1,0] neg_hi:[0,1,0]
	v_pk_mul_f32 v[34:35], v[2:3], v[138:139] op_sel:[0,0] op_sel_hi:[1,0]
	v_pk_fma_f32 v[6:7], v[128:129], v[198:199], v[6:7] op_sel:[0,0,0] op_sel_hi:[0,1,1] neg_lo:[0,1,0] neg_hi:[0,1,0]
	v_pk_fma_f32 v[34:35], v[4:5], v[138:139], v[34:35] op_sel:[0,1,0] op_sel_hi:[1,1,1]
	v_pk_fma_f32 v[8:9], v[128:129], v[198:199], v[8:9] op_sel:[1,0,0] op_sel_hi:[1,1,1] neg_lo:[0,1,0] neg_hi:[0,1,0]
	v_pk_fma_f32 v[34:35], v[6:7], v[140:141], v[34:35] op_sel:[0,0,0] op_sel_hi:[1,0,1]
	v_pk_fma_f32 v[34:35], v[8:9], v[140:141], v[34:35] op_sel:[0,1,0] op_sel_hi:[1,1,1]
	s_waitcnt lgkmcnt(0)
	ds_read_b128 v[134:137], v42 offset:46848
	ds_read_b128 v[130:133], v42 offset:46592
	ds_read_b64 v[142:143], v43 offset:46080
	ds_read_b128 v[122:125], v42 offset:46080
	ds_read_b128 v[126:129], v42 offset:46336
	ds_read_b128 v[138:141], v42 offset:47104
	v_pk_mul_f32 v[198:199], v[2:3], v[166:167] op_sel:[0,0] op_sel_hi:[1,0]
	v_pk_mul_f32 v[176:177], v[174:175], v[162:163] op_sel:[0,0] op_sel_hi:[1,0]
	v_pk_fma_f32 v[198:199], v[4:5], v[166:167], v[198:199] op_sel:[0,1,0] op_sel_hi:[1,1,1]
	v_pk_mul_f32 v[178:179], v[174:175], v[162:163] op_sel:[0,1] op_sel_hi:[1,1]
	v_pk_fma_f32 v[198:199], v[6:7], v[168:169], v[198:199] op_sel:[0,0,0] op_sel_hi:[1,0,1]
	v_pk_mul_f32 v[180:181], v[174:175], v[164:165] op_sel:[0,0] op_sel_hi:[1,0]
	v_pk_fma_f32 v[198:199], v[8:9], v[168:169], v[198:199] op_sel:[0,1,0] op_sel_hi:[1,1,1]
	v_pk_mul_f32 v[188:189], v[174:175], v[164:165] op_sel:[0,1] op_sel_hi:[1,1]
	v_pk_fma_f32 v[2:3], v[2:3], v[154:155], v[176:177] op_sel:[0,0,0] op_sel_hi:[1,0,1]
	v_add_f32_dpp v198, v198, v198 quad_perm:[1,0,3,2] row_mask:0xf bank_mask:0xf bound_ctrl:1
	v_add_f32_dpp v199, v199, v199 quad_perm:[1,0,3,2] row_mask:0xf bank_mask:0xf bound_ctrl:1
	v_pk_fma_f32 v[4:5], v[4:5], v[154:155], v[178:179] op_sel:[0,1,0] op_sel_hi:[1,1,1]
	v_add_f32_dpp v198, v198, v198 quad_perm:[2,3,0,1] row_mask:0xf bank_mask:0xf bound_ctrl:1
	v_add_f32_dpp v199, v199, v199 quad_perm:[2,3,0,1] row_mask:0xf bank_mask:0xf bound_ctrl:1
	v_pk_fma_f32 v[6:7], v[6:7], v[156:157], v[180:181] op_sel:[0,0,0] op_sel_hi:[1,0,1]
	v_add_f32_dpp v198, v198, v198 row_half_mirror row_mask:0xf bank_mask:0xf bound_ctrl:1
	v_add_f32_dpp v199, v199, v199 row_half_mirror row_mask:0xf bank_mask:0xf bound_ctrl:1
	v_pk_fma_f32 v[8:9], v[8:9], v[156:157], v[188:189] op_sel:[0,1,0] op_sel_hi:[1,1,1]
	v_add_f32_dpp v198, v198, v198 row_mirror row_mask:0xf bank_mask:0xf bound_ctrl:1
	v_add_f32_dpp v199, v199, v199 row_mirror row_mask:0xf bank_mask:0xf bound_ctrl:1
	v_pk_fma_f32 v[2:3], v[158:159], v[198:199], v[2:3] op_sel:[0,0,0] op_sel_hi:[0,1,1] neg_lo:[0,1,0] neg_hi:[0,1,0]
	v_pk_fma_f32 v[4:5], v[158:159], v[198:199], v[4:5] op_sel:[1,0,0] op_sel_hi:[1,1,1] neg_lo:[0,1,0] neg_hi:[0,1,0]
	v_pk_mul_f32 v[36:37], v[2:3], v[170:171] op_sel:[0,0] op_sel_hi:[1,0]
	v_pk_fma_f32 v[6:7], v[160:161], v[198:199], v[6:7] op_sel:[0,0,0] op_sel_hi:[0,1,1] neg_lo:[0,1,0] neg_hi:[0,1,0]
	v_pk_fma_f32 v[36:37], v[4:5], v[170:171], v[36:37] op_sel:[0,1,0] op_sel_hi:[1,1,1]
	v_pk_fma_f32 v[8:9], v[160:161], v[198:199], v[8:9] op_sel:[1,0,0] op_sel_hi:[1,1,1] neg_lo:[0,1,0] neg_hi:[0,1,0]
	v_pk_fma_f32 v[36:37], v[6:7], v[172:173], v[36:37] op_sel:[0,0,0] op_sel_hi:[1,0,1]
	v_pk_fma_f32 v[36:37], v[8:9], v[172:173], v[36:37] op_sel:[0,1,0] op_sel_hi:[1,1,1]
	s_waitcnt lgkmcnt(0)
	ds_read_b128 v[166:169], v42 offset:48384
	ds_read_b128 v[162:165], v42 offset:48128
	ds_read_b64 v[174:175], v43 offset:47616
	ds_read_b128 v[154:157], v42 offset:47616
	ds_read_b128 v[158:161], v42 offset:47872
	ds_read_b128 v[170:173], v42 offset:48640
	v_pk_mul_f32 v[198:199], v[2:3], v[134:135] op_sel:[0,0] op_sel_hi:[1,0]
	v_pk_mul_f32 v[176:177], v[142:143], v[130:131] op_sel:[0,0] op_sel_hi:[1,0]
	v_pk_fma_f32 v[198:199], v[4:5], v[134:135], v[198:199] op_sel:[0,1,0] op_sel_hi:[1,1,1]
	v_pk_mul_f32 v[178:179], v[142:143], v[130:131] op_sel:[0,1] op_sel_hi:[1,1]
	v_pk_fma_f32 v[198:199], v[6:7], v[136:137], v[198:199] op_sel:[0,0,0] op_sel_hi:[1,0,1]
	v_pk_mul_f32 v[180:181], v[142:143], v[132:133] op_sel:[0,0] op_sel_hi:[1,0]
	v_pk_fma_f32 v[198:199], v[8:9], v[136:137], v[198:199] op_sel:[0,1,0] op_sel_hi:[1,1,1]
	v_pk_mul_f32 v[188:189], v[142:143], v[132:133] op_sel:[0,1] op_sel_hi:[1,1]
	v_pk_fma_f32 v[2:3], v[2:3], v[122:123], v[176:177] op_sel:[0,0,0] op_sel_hi:[1,0,1]
	v_add_f32_dpp v198, v198, v198 quad_perm:[1,0,3,2] row_mask:0xf bank_mask:0xf bound_ctrl:1
	v_add_f32_dpp v199, v199, v199 quad_perm:[1,0,3,2] row_mask:0xf bank_mask:0xf bound_ctrl:1
	v_pk_fma_f32 v[4:5], v[4:5], v[122:123], v[178:179] op_sel:[0,1,0] op_sel_hi:[1,1,1]
	v_add_f32_dpp v198, v198, v198 quad_perm:[2,3,0,1] row_mask:0xf bank_mask:0xf bound_ctrl:1
	v_add_f32_dpp v199, v199, v199 quad_perm:[2,3,0,1] row_mask:0xf bank_mask:0xf bound_ctrl:1
	v_pk_fma_f32 v[6:7], v[6:7], v[124:125], v[180:181] op_sel:[0,0,0] op_sel_hi:[1,0,1]
	v_add_f32_dpp v198, v198, v198 row_half_mirror row_mask:0xf bank_mask:0xf bound_ctrl:1
	v_add_f32_dpp v199, v199, v199 row_half_mirror row_mask:0xf bank_mask:0xf bound_ctrl:1
	v_pk_fma_f32 v[8:9], v[8:9], v[124:125], v[188:189] op_sel:[0,1,0] op_sel_hi:[1,1,1]
	v_add_f32_dpp v198, v198, v198 row_mirror row_mask:0xf bank_mask:0xf bound_ctrl:1
	v_add_f32_dpp v199, v199, v199 row_mirror row_mask:0xf bank_mask:0xf bound_ctrl:1
	v_pk_fma_f32 v[2:3], v[126:127], v[198:199], v[2:3] op_sel:[0,0,0] op_sel_hi:[0,1,1] neg_lo:[0,1,0] neg_hi:[0,1,0]
	v_pk_fma_f32 v[4:5], v[126:127], v[198:199], v[4:5] op_sel:[1,0,0] op_sel_hi:[1,1,1] neg_lo:[0,1,0] neg_hi:[0,1,0]
	v_pk_mul_f32 v[38:39], v[2:3], v[138:139] op_sel:[0,0] op_sel_hi:[1,0]
	v_pk_fma_f32 v[6:7], v[128:129], v[198:199], v[6:7] op_sel:[0,0,0] op_sel_hi:[0,1,1] neg_lo:[0,1,0] neg_hi:[0,1,0]
	v_pk_fma_f32 v[38:39], v[4:5], v[138:139], v[38:39] op_sel:[0,1,0] op_sel_hi:[1,1,1]
	v_pk_fma_f32 v[8:9], v[128:129], v[198:199], v[8:9] op_sel:[1,0,0] op_sel_hi:[1,1,1] neg_lo:[0,1,0] neg_hi:[0,1,0]
	v_pk_fma_f32 v[38:39], v[6:7], v[140:141], v[38:39] op_sel:[0,0,0] op_sel_hi:[1,0,1]
	v_pk_fma_f32 v[38:39], v[8:9], v[140:141], v[38:39] op_sel:[0,1,0] op_sel_hi:[1,1,1]
	s_waitcnt lgkmcnt(0)
	v_pk_mul_f32 v[198:199], v[2:3], v[166:167] op_sel:[0,0] op_sel_hi:[1,0]
	v_pk_mul_f32 v[176:177], v[174:175], v[162:163] op_sel:[0,0] op_sel_hi:[1,0]
	v_pk_fma_f32 v[198:199], v[4:5], v[166:167], v[198:199] op_sel:[0,1,0] op_sel_hi:[1,1,1]
	v_pk_mul_f32 v[178:179], v[174:175], v[162:163] op_sel:[0,1] op_sel_hi:[1,1]
	v_pk_fma_f32 v[198:199], v[6:7], v[168:169], v[198:199] op_sel:[0,0,0] op_sel_hi:[1,0,1]
	v_pk_mul_f32 v[180:181], v[174:175], v[164:165] op_sel:[0,0] op_sel_hi:[1,0]
	v_pk_fma_f32 v[198:199], v[8:9], v[168:169], v[198:199] op_sel:[0,1,0] op_sel_hi:[1,1,1]
	v_pk_mul_f32 v[188:189], v[174:175], v[164:165] op_sel:[0,1] op_sel_hi:[1,1]
	v_pk_fma_f32 v[2:3], v[2:3], v[154:155], v[176:177] op_sel:[0,0,0] op_sel_hi:[1,0,1]
	v_add_f32_dpp v198, v198, v198 quad_perm:[1,0,3,2] row_mask:0xf bank_mask:0xf bound_ctrl:1
	v_add_f32_dpp v199, v199, v199 quad_perm:[1,0,3,2] row_mask:0xf bank_mask:0xf bound_ctrl:1
	v_pk_fma_f32 v[4:5], v[4:5], v[154:155], v[178:179] op_sel:[0,1,0] op_sel_hi:[1,1,1]
	v_add_f32_dpp v198, v198, v198 quad_perm:[2,3,0,1] row_mask:0xf bank_mask:0xf bound_ctrl:1
	v_add_f32_dpp v199, v199, v199 quad_perm:[2,3,0,1] row_mask:0xf bank_mask:0xf bound_ctrl:1
	v_pk_fma_f32 v[6:7], v[6:7], v[156:157], v[180:181] op_sel:[0,0,0] op_sel_hi:[1,0,1]
	v_add_f32_dpp v198, v198, v198 row_half_mirror row_mask:0xf bank_mask:0xf bound_ctrl:1
	v_add_f32_dpp v199, v199, v199 row_half_mirror row_mask:0xf bank_mask:0xf bound_ctrl:1
	v_pk_fma_f32 v[8:9], v[8:9], v[156:157], v[188:189] op_sel:[0,1,0] op_sel_hi:[1,1,1]
	v_add_f32_dpp v198, v198, v198 row_mirror row_mask:0xf bank_mask:0xf bound_ctrl:1
	v_add_f32_dpp v199, v199, v199 row_mirror row_mask:0xf bank_mask:0xf bound_ctrl:1
	v_pk_fma_f32 v[2:3], v[158:159], v[198:199], v[2:3] op_sel:[0,0,0] op_sel_hi:[0,1,1] neg_lo:[0,1,0] neg_hi:[0,1,0]
	v_pk_fma_f32 v[4:5], v[158:159], v[198:199], v[4:5] op_sel:[1,0,0] op_sel_hi:[1,1,1] neg_lo:[0,1,0] neg_hi:[0,1,0]
	v_pk_mul_f32 v[40:41], v[2:3], v[170:171] op_sel:[0,0] op_sel_hi:[1,0]
	v_pk_fma_f32 v[6:7], v[160:161], v[198:199], v[6:7] op_sel:[0,0,0] op_sel_hi:[0,1,1] neg_lo:[0,1,0] neg_hi:[0,1,0]
	v_pk_fma_f32 v[40:41], v[4:5], v[170:171], v[40:41] op_sel:[0,1,0] op_sel_hi:[1,1,1]
	v_pk_fma_f32 v[8:9], v[160:161], v[198:199], v[8:9] op_sel:[1,0,0] op_sel_hi:[1,1,1] neg_lo:[0,1,0] neg_hi:[0,1,0]
	v_pk_fma_f32 v[40:41], v[6:7], v[172:173], v[40:41] op_sel:[0,0,0] op_sel_hi:[1,0,1]
	v_pk_fma_f32 v[40:41], v[8:9], v[172:173], v[40:41] op_sel:[0,1,0] op_sel_hi:[1,1,1]
	v_add_f32_dpp v190, v10, v10 row_mirror row_mask:0xf bank_mask:0x3
	v_add_f32_dpp v190, v26, v26 row_mirror row_mask:0xf bank_mask:0xc
	v_add_f32_dpp v191, v12, v12 row_mirror row_mask:0xf bank_mask:0x3
	v_add_f32_dpp v191, v28, v28 row_mirror row_mask:0xf bank_mask:0xc
	v_add_f32_dpp v192, v14, v14 row_mirror row_mask:0xf bank_mask:0x3
	v_add_f32_dpp v192, v30, v30 row_mirror row_mask:0xf bank_mask:0xc
	v_add_f32_dpp v193, v16, v16 row_mirror row_mask:0xf bank_mask:0x3
	v_add_f32_dpp v193, v32, v32 row_mirror row_mask:0xf bank_mask:0xc
	v_add_f32_dpp v194, v18, v18 row_mirror row_mask:0xf bank_mask:0x3
	v_add_f32_dpp v194, v34, v34 row_mirror row_mask:0xf bank_mask:0xc
	v_add_f32_dpp v195, v20, v20 row_mirror row_mask:0xf bank_mask:0x3
	v_add_f32_dpp v195, v36, v36 row_mirror row_mask:0xf bank_mask:0xc
	v_add_f32_dpp v196, v22, v22 row_mirror row_mask:0xf bank_mask:0x3
	v_add_f32_dpp v196, v38, v38 row_mirror row_mask:0xf bank_mask:0xc
	v_add_f32_dpp v197, v24, v24 row_mirror row_mask:0xf bank_mask:0x3
	v_add_f32_dpp v197, v40, v40 row_mirror row_mask:0xf bank_mask:0xc
	v_add_f32_dpp v202, v190, v190 row_half_mirror row_mask:0xf bank_mask:0x5
	v_add_f32_dpp v202, v194, v194 row_half_mirror row_mask:0xf bank_mask:0xa
	v_add_f32_dpp v203, v191, v191 row_half_mirror row_mask:0xf bank_mask:0x5
	v_add_f32_dpp v203, v195, v195 row_half_mirror row_mask:0xf bank_mask:0xa
	v_add_f32_dpp v204, v192, v192 row_half_mirror row_mask:0xf bank_mask:0x5
	v_add_f32_dpp v204, v196, v196 row_half_mirror row_mask:0xf bank_mask:0xa
	v_add_f32_dpp v205, v193, v193 row_half_mirror row_mask:0xf bank_mask:0x5
	v_add_f32_dpp v205, v197, v197 row_half_mirror row_mask:0xf bank_mask:0xa
	v_cndmask_b32_e64 v176, v202, v204, s[84:85]
	v_cndmask_b32_e64 v177, v204, v202, s[84:85]
	v_cndmask_b32_e64 v178, v203, v205, s[84:85]
	v_cndmask_b32_e64 v179, v205, v203, s[84:85]
	s_nop 1
	v_add_f32_dpp v210, v177, v176 quad_perm:[2,3,0,1] row_mask:0xf bank_mask:0xf bound_ctrl:1
	v_add_f32_dpp v211, v179, v178 quad_perm:[2,3,0,1] row_mask:0xf bank_mask:0xf bound_ctrl:1
	s_nop 0
	v_cndmask_b32_e64 v176, v210, v211, s[88:89]
	v_cndmask_b32_e64 v177, v211, v210, s[88:89]
	s_nop 1
	v_add_f32_dpp v212, v177, v176 quad_perm:[1,0,3,2] row_mask:0xf bank_mask:0xf bound_ctrl:1
	ds_write_b32 v44, v212 offset:2304
	v_add_f32_dpp v190, v11, v11 row_mirror row_mask:0xf bank_mask:0x3
	v_add_f32_dpp v190, v27, v27 row_mirror row_mask:0xf bank_mask:0xc
	v_add_f32_dpp v191, v13, v13 row_mirror row_mask:0xf bank_mask:0x3
	v_add_f32_dpp v191, v29, v29 row_mirror row_mask:0xf bank_mask:0xc
	v_add_f32_dpp v192, v15, v15 row_mirror row_mask:0xf bank_mask:0x3
	v_add_f32_dpp v192, v31, v31 row_mirror row_mask:0xf bank_mask:0xc
	v_add_f32_dpp v193, v17, v17 row_mirror row_mask:0xf bank_mask:0x3
	v_add_f32_dpp v193, v33, v33 row_mirror row_mask:0xf bank_mask:0xc
	v_add_f32_dpp v194, v19, v19 row_mirror row_mask:0xf bank_mask:0x3
	v_add_f32_dpp v194, v35, v35 row_mirror row_mask:0xf bank_mask:0xc
	v_add_f32_dpp v195, v21, v21 row_mirror row_mask:0xf bank_mask:0x3
	v_add_f32_dpp v195, v37, v37 row_mirror row_mask:0xf bank_mask:0xc
	v_add_f32_dpp v196, v23, v23 row_mirror row_mask:0xf bank_mask:0x3
	v_add_f32_dpp v196, v39, v39 row_mirror row_mask:0xf bank_mask:0xc
	v_add_f32_dpp v197, v25, v25 row_mirror row_mask:0xf bank_mask:0x3
	v_add_f32_dpp v197, v41, v41 row_mirror row_mask:0xf bank_mask:0xc
	v_add_f32_dpp v202, v190, v190 row_half_mirror row_mask:0xf bank_mask:0x5
	v_add_f32_dpp v202, v194, v194 row_half_mirror row_mask:0xf bank_mask:0xa
	v_add_f32_dpp v203, v191, v191 row_half_mirror row_mask:0xf bank_mask:0x5
	v_add_f32_dpp v203, v195, v195 row_half_mirror row_mask:0xf bank_mask:0xa
	v_add_f32_dpp v204, v192, v192 row_half_mirror row_mask:0xf bank_mask:0x5
	v_add_f32_dpp v204, v196, v196 row_half_mirror row_mask:0xf bank_mask:0xa
	v_add_f32_dpp v205, v193, v193 row_half_mirror row_mask:0xf bank_mask:0x5
	v_add_f32_dpp v205, v197, v197 row_half_mirror row_mask:0xf bank_mask:0xa
	v_cndmask_b32_e64 v176, v202, v204, s[84:85]
	v_cndmask_b32_e64 v177, v204, v202, s[84:85]
	v_cndmask_b32_e64 v178, v203, v205, s[84:85]
	v_cndmask_b32_e64 v179, v205, v203, s[84:85]
	s_nop 1
	v_add_f32_dpp v210, v177, v176 quad_perm:[2,3,0,1] row_mask:0xf bank_mask:0xf bound_ctrl:1
	v_add_f32_dpp v211, v179, v178 quad_perm:[2,3,0,1] row_mask:0xf bank_mask:0xf bound_ctrl:1
	s_nop 0
	v_cndmask_b32_e64 v176, v210, v211, s[88:89]
	v_cndmask_b32_e64 v177, v211, v210, s[88:89]
	s_nop 1
	v_add_f32_dpp v212, v177, v176 quad_perm:[1,0,3,2] row_mask:0xf bank_mask:0xf bound_ctrl:1
	ds_write_b32 v44, v212 offset:2308
	v_xor_b32_e32 v42, 0xc000, v42
	v_xor_b32_e32 v43, 0xc000, v43
	v_xor_b32_e32 v44, 0x2000, v44
	s_branch .Lrc_join
